# phase 3 row pass fused into the GEMM2 phase (per-M-tile counters, device-scope release/acquire), rows w, w+8.. per wave, placement-matched with one s_nop; on the rolled lora copy loop
# baseline (speedup 1.0000x reference)
; __device__ __forceinline__ const float* xrow_ptr(const Ctx& p, int row) { return row < MPR ? p.in(0) + (size_t)row * DM : p.in(1) + (size_t)(row - MPR) * DM; }
; __device__ __forceinline__ void phase_rowpass(const Ctx& p, const float* F, int base_is_x, float alpha, const float* gpost, const float* gnext, bf16_t* XN, const float* PART, int nsplit) {
;     ...
;     auto loadrow = [&](int m, f32x4 (&f)[4], f32x4 (&b)[4]) {
;         const f32x4* fr = (const f32x4*)(F + (size_t)m * DM) + lane;
;         const f32x4* br = (const f32x4*)(base_is_x ? xrow_ptr(p, m) : H + (size_t)m * DM) + lane;
; #pragma unroll
;         for (int j = 0; j < 4; ++j) { b[j] = br[64 * j];
;             if (m < MPR) f[j] = fr[64 * j];
;             else { f[j] = (f32x4){0.f, 0.f, 0.f, 0.f};
;                 for (int ks = 0; ks < nsplit; ++ks) f[j] = f[j] + ((const f32x4*)(PART + ((size_t)ks * 128 + (m - MPR)) * DM))[lane + 64 * j]; } }
;     };
;     f32x4 gp[4], gn[4];
; #pragma unroll
;     for (int j = 0; j < 4; ++j) { gp[j] = ((const f32x4*)gpost)[lane + 64 * j]; gn[j] = gnext ? ((const f32x4*)gnext)[lane + 64 * j] : (f32x4){0.f, 0.f, 0.f, 0.f}; }
;     f32x4 f[4], b[4], f2[4], b2[4];
;     if (gw < MR) loadrow(gw, f, b);
;     for (int m = gw; m < MR; m += NGW) {
;         const bool more = m + NGW < MR;
;         if (more) loadrow(m + NGW, f2, b2);
;         float s = 0.f;
; #pragma unroll
;         for (int j = 0; j < 4; ++j) s += (f[j].x * f[j].x + f[j].y * f[j].y) + (f[j].z * f[j].z + f[j].w * f[j].w);
;         const float rs = alpha / sqrtf(wave_sum_fast(s) * (1.f / DM) + EPS);
;         float s2 = 0.f;
; #pragma unroll
;         for (int j = 0; j < 4; ++j) { b[j] = b[j] + f[j] * rs * gp[j]; s2 += (b[j].x * b[j].x + b[j].y * b[j].y) + (b[j].z * b[j].z + b[j].w * b[j].w);
;             ((f32x4*)(H + (size_t)m * DM))[lane + 64 * j] = b[j]; }
.Lfrp3_wa_done:
	s_or_b64 exec, exec, s[46:47]
	s_barrier
	s_and_b32 s42, s28, 7
	s_lshl_b32 s42, s42, 3
	s_bfe_u32 s43, s28, 0x30003
	s_add_i32 s42, s42, s43
	s_lshr_b32 s43, s28, 6
	s_lshl_b32 s42, s42, 8
	s_lshl_b32 s43, s43, 6
	s_add_i32 s42, s42, s43
	s_mov_b32 s43, s20
	s_add_i32 s23, s42, s43
	s_lshl_b32 s21, s23, 12
	s_add_u32 s40, s8, s21
	s_addc_u32 s41, s9, 0
	s_lshl_b32 s22, s23, 11
	s_add_u32 s42, s30, s22
	s_addc_u32 s43, s31, 0
	s_add_u32 s42, s42, 0x3200000
	s_addc_u32 s43, s43, 0
	s_add_u32 s24, s30, s21
	s_addc_u32 s25, s31, 0
	s_add_u32 s24, s24, 0xabe0000
	s_addc_u32 s25, s25, 0
	s_add_u32 s26, s14, s21
	s_addc_u32 s27, s15, 0
	global_load_dwordx4 v[0:3], v144, s[24:25] offset:0
	global_load_dwordx4 v[4:7], v144, s[24:25] offset:1024
	global_load_dwordx4 v[8:11], v144, s[24:25] offset:2048
	global_load_dwordx4 v[12:15], v144, s[24:25] offset:3072
	global_load_dwordx4 v[16:19], v144, s[26:27] offset:0
	global_load_dwordx4 v[20:23], v144, s[26:27] offset:1024
	global_load_dwordx4 v[24:27], v144, s[26:27] offset:2048
	global_load_dwordx4 v[28:31], v144, s[26:27] offset:3072
	s_add_u32 s24, s24, 0x8000
	s_addc_u32 s25, s25, 0
	s_add_u32 s26, s26, 0x8000
	s_addc_u32 s27, s27, 0
	global_load_dwordx4 v[32:35], v144, s[24:25] offset:0
	global_load_dwordx4 v[36:39], v144, s[24:25] offset:1024
	global_load_dwordx4 v[40:43], v144, s[24:25] offset:2048
	global_load_dwordx4 v[44:47], v144, s[24:25] offset:3072
	global_load_dwordx4 v[48:51], v144, s[26:27] offset:0
	global_load_dwordx4 v[52:55], v144, s[26:27] offset:1024
	global_load_dwordx4 v[56:59], v144, s[26:27] offset:2048
	global_load_dwordx4 v[60:63], v144, s[26:27] offset:3072
	s_add_u32 s24, s24, 0x8000
	s_addc_u32 s25, s25, 0
	s_add_u32 s26, s26, 0x8000
	s_addc_u32 s27, s27, 0
	global_load_dwordx4 v[64:67], v144, s[24:25] offset:0
	global_load_dwordx4 v[68:71], v144, s[24:25] offset:1024
	global_load_dwordx4 v[72:75], v144, s[24:25] offset:2048
	global_load_dwordx4 v[76:79], v144, s[24:25] offset:3072
	global_load_dwordx4 v[80:83], v144, s[26:27] offset:0
	global_load_dwordx4 v[84:87], v144, s[26:27] offset:1024
	global_load_dwordx4 v[88:91], v144, s[26:27] offset:2048
	global_load_dwordx4 v[92:95], v144, s[26:27] offset:3072
	s_add_u32 s24, s24, 0x8000
	s_addc_u32 s25, s25, 0
	s_add_u32 s26, s26, 0x8000
	s_addc_u32 s27, s27, 0
	s_waitcnt vmcnt(16)
	v_mul_f32_e32 v96, v1, v1
	v_mul_f32_e32 v98, v3, v3
	v_fmac_f32_e32 v96, v0, v0
	v_fmac_f32_e32 v98, v2, v2
	v_add_f32_e32 v96, v96, v98
	v_mul_f32_e32 v97, v5, v5
	v_mul_f32_e32 v98, v7, v7
	v_fmac_f32_e32 v97, v4, v4
	v_fmac_f32_e32 v98, v6, v6
	v_add_f32_e32 v97, v97, v98
	v_add_f32_e32 v96, v97, v96
	v_mul_f32_e32 v97, v9, v9
	v_mul_f32_e32 v98, v11, v11
	v_fmac_f32_e32 v97, v8, v8
	v_fmac_f32_e32 v98, v10, v10
	v_add_f32_e32 v97, v97, v98
	v_add_f32_e32 v96, v97, v96
	v_mul_f32_e32 v97, v13, v13
	v_mul_f32_e32 v98, v15, v15
	v_fmac_f32_e32 v97, v12, v12
	v_fmac_f32_e32 v98, v14, v14
	v_add_f32_e32 v97, v97, v98
	v_add_f32_e32 v96, v97, v96
	s_nop 1
	v_add_f32_dpp v96, v96, v96 quad_perm:[1,0,3,2] row_mask:0xf bank_mask:0xf bound_ctrl:1
	s_nop 1
	v_add_f32_dpp v96, v96, v96 quad_perm:[2,3,0,1] row_mask:0xf bank_mask:0xf bound_ctrl:1
	s_nop 1
	v_add_f32_dpp v96, v96, v96 row_half_mirror row_mask:0xf bank_mask:0xf bound_ctrl:1
	s_nop 1
	v_add_f32_dpp v96, v96, v96 row_mirror row_mask:0xf bank_mask:0xf bound_ctrl:1
	v_mov_b32_e32 v97, v96
	s_nop 1
	v_permlane16_swap_b32_e32 v96, v97
	v_add_f32_e32 v96, v96, v97
	v_mov_b32_e32 v97, v96
	s_nop 1
	v_permlane32_swap_b32_e32 v96, v97
	v_add_f32_e32 v96, v96, v97
	v_fmamk_f32 v96, v96, 0x3a800000, v146
	v_mul_f32_e32 v97, 0x4f800000, v96
	v_cmp_gt_f32_e32 vcc, s33, v96
	s_nop 1
	v_cndmask_b32_e32 v96, v96, v97, vcc
	v_sqrt_f32_e32 v97, v96
	s_nop 0
	v_add_u32_e32 v98, -1, v97
	v_fma_f32 v99, -v98, v97, v96
	v_cmp_ge_f32_e64 s[4:5], 0, v99
	v_add_u32_e32 v99, 1, v97
	s_nop 0
	v_cndmask_b32_e64 v98, v97, v98, s[4:5]
	v_fma_f32 v97, -v99, v97, v96
	v_cmp_lt_f32_e64 s[4:5], 0, v97
	s_nop 1
	v_cndmask_b32_e64 v97, v98, v99, s[4:5]
	v_mul_f32_e32 v98, 0x37800000, v97
	v_cndmask_b32_e32 v97, v97, v98, vcc
	v_cmp_class_f32_e32 vcc, v96, v147
	s_nop 1
	v_cndmask_b32_e32 v96, v97, v96, vcc
	v_div_scale_f32 v97, s[4:5], v96, v96, 0.5
	v_rcp_f32_e32 v98, v97
	s_nop 0
	v_fma_f32 v99, -v97, v98, 1.0
	v_fmac_f32_e32 v98, v99, v98
	v_div_scale_f32 v99, vcc, 0.5, v96, 0.5
	v_mul_f32_e32 v100, v99, v98
	v_fma_f32 v101, -v97, v100, v99
	v_fmac_f32_e32 v100, v101, v98
	v_fma_f32 v97, -v97, v100, v99
	v_div_fmas_f32 v97, v97, v98, v100
	v_div_fixup_f32 v96, v97, v96, 0.5
	v_mul_f32_e32 v0, v0, v96
	v_mul_f32_e32 v1, v1, v96
	v_mul_f32_e32 v2, v2, v96
	v_mul_f32_e32 v3, v3, v96
	v_mul_f32_e32 v4, v4, v96
	v_mul_f32_e32 v5, v5, v96
	v_mul_f32_e32 v6, v6, v96
	v_mul_f32_e32 v7, v7, v96
	v_mul_f32_e32 v8, v8, v96
	v_mul_f32_e32 v9, v9, v96
	v_mul_f32_e32 v10, v10, v96
	v_mul_f32_e32 v11, v11, v96
	v_mul_f32_e32 v12, v12, v96
	v_mul_f32_e32 v13, v13, v96
	v_mul_f32_e32 v14, v14, v96
	v_mul_f32_e32 v15, v15, v96
	v_fmac_f32_e32 v16, v112, v0
	v_fmac_f32_e32 v17, v113, v1
	v_fmac_f32_e32 v18, v114, v2
	v_fmac_f32_e32 v19, v115, v3
	v_fmac_f32_e32 v20, v116, v4
	v_fmac_f32_e32 v21, v117, v5
	v_fmac_f32_e32 v22, v118, v6
	v_fmac_f32_e32 v23, v119, v7
	v_fmac_f32_e32 v24, v120, v8
	v_fmac_f32_e32 v25, v121, v9
	v_fmac_f32_e32 v26, v122, v10
	v_fmac_f32_e32 v27, v123, v11
	v_fmac_f32_e32 v28, v124, v12
	v_fmac_f32_e32 v29, v125, v13
	v_fmac_f32_e32 v30, v126, v14
	v_fmac_f32_e32 v31, v127, v15
	global_store_dwordx4 v144, v[16:19], s[40:41] offset:0
	global_store_dwordx4 v144, v[20:23], s[40:41] offset:1024
; __device__ __forceinline__ unsigned pk2(float lo, float hi) { f32x2 v = {lo, hi}; bf16x2_t b = __builtin_convertvector(v, bf16x2_t); return __builtin_bit_cast(unsigned, b); }
; __device__ __forceinline__ void phase_rowpass(const Ctx& p, const float* F, int base_is_x, float alpha, const float* gpost, const float* gnext, bf16_t* XN, const float* PART, int nsplit) {
;     ...
;     for (int m = gw; m < MR; m += NGW) {
;         const bool more = m + NGW < MR;
;         if (more) loadrow(m + NGW, f2, b2);
;         float s = 0.f;
; #pragma unroll
;         for (int j = 0; j < 4; ++j) s += (f[j].x * f[j].x + f[j].y * f[j].y) + (f[j].z * f[j].z + f[j].w * f[j].w);
;         const float rs = alpha / sqrtf(wave_sum_fast(s) * (1.f / DM) + EPS);
;         float s2 = 0.f;
; #pragma unroll
;         for (int j = 0; j < 4; ++j) { b[j] = b[j] + f[j] * rs * gp[j]; s2 += (b[j].x * b[j].x + b[j].y * b[j].y) + (b[j].z * b[j].z + b[j].w * b[j].w);
;             ((f32x4*)(H + (size_t)m * DM))[lane + 64 * j] = b[j]; }
;         if (gnext) {
;             const float r2 = 1.f / sqrtf(wave_sum_fast(s2) * (1.f / DM) + EPS);
;             u32x2* o8 = (u32x2*)(XN + (size_t)m * DM) + lane;
; #pragma unroll
;             for (int j = 0; j < 4; ++j) { u32x2 w; w.x = pk2(b[j].x * r2 * gn[j].x, b[j].y * r2 * gn[j].y); w.y = pk2(b[j].z * r2 * gn[j].z, b[j].w * r2 * gn[j].w); o8[64 * j] = w; }
;         }
;         if (more) {
; #pragma unroll
;             for (int j = 0; j < 4; ++j) { f[j] = f2[j]; b[j] = b2[j]; } }
	global_store_dwordx4 v144, v[24:27], s[40:41] offset:2048
	global_store_dwordx4 v144, v[28:31], s[40:41] offset:3072
	v_mul_f32_e32 v96, v17, v17
	v_mul_f32_e32 v98, v19, v19
	v_fmac_f32_e32 v96, v16, v16
	v_fmac_f32_e32 v98, v18, v18
	v_add_f32_e32 v96, v96, v98
	v_mul_f32_e32 v97, v21, v21
	v_mul_f32_e32 v98, v23, v23
	v_fmac_f32_e32 v97, v20, v20
	v_fmac_f32_e32 v98, v22, v22
	v_add_f32_e32 v97, v97, v98
	v_add_f32_e32 v96, v97, v96
	v_mul_f32_e32 v97, v25, v25
	v_mul_f32_e32 v98, v27, v27
	v_fmac_f32_e32 v97, v24, v24
	v_fmac_f32_e32 v98, v26, v26
	v_add_f32_e32 v97, v97, v98
	v_add_f32_e32 v96, v97, v96
	v_mul_f32_e32 v97, v29, v29
	v_mul_f32_e32 v98, v31, v31
	v_fmac_f32_e32 v97, v28, v28
	v_fmac_f32_e32 v98, v30, v30
	v_add_f32_e32 v97, v97, v98
	v_add_f32_e32 v96, v97, v96
	s_nop 1
	v_add_f32_dpp v96, v96, v96 quad_perm:[1,0,3,2] row_mask:0xf bank_mask:0xf bound_ctrl:1
	s_nop 1
	v_add_f32_dpp v96, v96, v96 quad_perm:[2,3,0,1] row_mask:0xf bank_mask:0xf bound_ctrl:1
	s_nop 1
	v_add_f32_dpp v96, v96, v96 row_half_mirror row_mask:0xf bank_mask:0xf bound_ctrl:1
	s_nop 1
	v_add_f32_dpp v96, v96, v96 row_mirror row_mask:0xf bank_mask:0xf bound_ctrl:1
	v_mov_b32_e32 v97, v96
	s_nop 1
	v_permlane16_swap_b32_e32 v96, v97
	v_add_f32_e32 v96, v96, v97
	v_mov_b32_e32 v97, v96
	s_nop 1
	v_permlane32_swap_b32_e32 v96, v97
	v_add_f32_e32 v96, v96, v97
	v_fmamk_f32 v96, v96, 0x3a800000, v146
	v_mul_f32_e32 v97, 0x4f800000, v96
	v_cmp_gt_f32_e32 vcc, s33, v96
	s_nop 1
	v_cndmask_b32_e32 v96, v96, v97, vcc
	v_sqrt_f32_e32 v97, v96
	s_nop 0
	v_add_u32_e32 v98, -1, v97
	v_fma_f32 v99, -v98, v97, v96
	v_cmp_ge_f32_e64 s[4:5], 0, v99
	v_add_u32_e32 v99, 1, v97
	s_nop 0
	v_cndmask_b32_e64 v98, v97, v98, s[4:5]
	v_fma_f32 v97, -v99, v97, v96
	v_cmp_lt_f32_e64 s[4:5], 0, v97
	s_nop 1
	v_cndmask_b32_e64 v97, v98, v99, s[4:5]
	v_mul_f32_e32 v98, 0x37800000, v97
	v_cndmask_b32_e32 v97, v97, v98, vcc
	v_cmp_class_f32_e32 vcc, v96, v147
	s_nop 1
	v_cndmask_b32_e32 v96, v97, v96, vcc
	v_div_scale_f32 v97, s[4:5], v96, v96, 1.0
	v_rcp_f32_e32 v98, v97
	s_nop 0
	v_fma_f32 v99, -v97, v98, 1.0
	v_fmac_f32_e32 v98, v99, v98
	v_div_scale_f32 v99, vcc, 1.0, v96, 1.0
	v_mul_f32_e32 v100, v99, v98
	v_fma_f32 v101, -v97, v100, v99
	v_fmac_f32_e32 v100, v101, v98
	v_fma_f32 v97, -v97, v100, v99
	v_div_fmas_f32 v97, v97, v98, v100
	v_div_fixup_f32 v96, v97, v96, 1.0
	v_mul_f32_e32 v0, v16, v96
	v_mul_f32_e32 v1, v17, v96
	v_mul_f32_e32 v2, v18, v96
	v_mul_f32_e32 v3, v19, v96
	v_mul_f32_e32 v4, v20, v96
	v_mul_f32_e32 v5, v21, v96
	v_mul_f32_e32 v6, v22, v96
	v_mul_f32_e32 v7, v23, v96
	v_mul_f32_e32 v8, v24, v96
	v_mul_f32_e32 v9, v25, v96
	v_mul_f32_e32 v10, v26, v96
	v_mul_f32_e32 v11, v27, v96
	v_mul_f32_e32 v12, v28, v96
	v_mul_f32_e32 v13, v29, v96
	v_mul_f32_e32 v14, v30, v96
	v_mul_f32_e32 v15, v31, v96
	v_mul_f32_e32 v0, v128, v0
	v_mul_f32_e32 v1, v129, v1
	v_mul_f32_e32 v2, v130, v2
	v_mul_f32_e32 v3, v131, v3
	v_mul_f32_e32 v4, v132, v4
	v_mul_f32_e32 v5, v133, v5
	v_mul_f32_e32 v6, v134, v6
	v_mul_f32_e32 v7, v135, v7
	v_mul_f32_e32 v8, v136, v8
	v_mul_f32_e32 v9, v137, v9
	v_mul_f32_e32 v10, v138, v10
	v_mul_f32_e32 v11, v139, v11
	v_mul_f32_e32 v12, v140, v12
	v_mul_f32_e32 v13, v141, v13
	v_mul_f32_e32 v14, v142, v14
	v_mul_f32_e32 v15, v143, v15
	v_cvt_pk_bf16_f32 v148, v0, v1
	v_cvt_pk_bf16_f32 v149, v2, v3
	global_store_dwordx2 v145, v[148:149], s[42:43] offset:0
	v_cvt_pk_bf16_f32 v150, v4, v5
	v_cvt_pk_bf16_f32 v151, v6, v7
	global_store_dwordx2 v145, v[150:151], s[42:43] offset:512
	v_cvt_pk_bf16_f32 v152, v8, v9
	v_cvt_pk_bf16_f32 v153, v10, v11
	global_store_dwordx2 v145, v[152:153], s[42:43] offset:1024
	v_cvt_pk_bf16_f32 v154, v12, v13
	v_cvt_pk_bf16_f32 v155, v14, v15
	global_store_dwordx2 v145, v[154:155], s[42:43] offset:1536
	s_add_u32 s40, s40, 0x8000
	s_addc_u32 s41, s41, 0
	s_add_u32 s42, s42, 0x4000
	s_addc_u32 s43, s43, 0
	global_load_dwordx4 v[0:3], v144, s[24:25] offset:0
	global_load_dwordx4 v[4:7], v144, s[24:25] offset:1024
	global_load_dwordx4 v[8:11], v144, s[24:25] offset:2048
	global_load_dwordx4 v[12:15], v144, s[24:25] offset:3072
	global_load_dwordx4 v[16:19], v144, s[26:27] offset:0
	global_load_dwordx4 v[20:23], v144, s[26:27] offset:1024
	global_load_dwordx4 v[24:27], v144, s[26:27] offset:2048
	global_load_dwordx4 v[28:31], v144, s[26:27] offset:3072
	s_add_u32 s24, s24, 0x8000
	s_addc_u32 s25, s25, 0
	s_add_u32 s26, s26, 0x8000
	s_addc_u32 s27, s27, 0
	s_waitcnt vmcnt(24)
; __device__ __forceinline__ unsigned pk2(float lo, float hi) { f32x2 v = {lo, hi}; bf16x2_t b = __builtin_convertvector(v, bf16x2_t); return __builtin_bit_cast(unsigned, b); }
; __device__ __forceinline__ void phase_rowpass(const Ctx& p, const float* F, int base_is_x, float alpha, const float* gpost, const float* gnext, bf16_t* XN, const float* PART, int nsplit) {
;     ...
;     for (int m = gw; m < MR; m += NGW) {
;         const bool more = m + NGW < MR;
;         if (more) loadrow(m + NGW, f2, b2);
;         float s = 0.f;
; #pragma unroll
;         for (int j = 0; j < 4; ++j) s += (f[j].x * f[j].x + f[j].y * f[j].y) + (f[j].z * f[j].z + f[j].w * f[j].w);
;         const float rs = alpha / sqrtf(wave_sum_fast(s) * (1.f / DM) + EPS);
;         float s2 = 0.f;
; #pragma unroll
;         for (int j = 0; j < 4; ++j) { b[j] = b[j] + f[j] * rs * gp[j]; s2 += (b[j].x * b[j].x + b[j].y * b[j].y) + (b[j].z * b[j].z + b[j].w * b[j].w);
;             ((f32x4*)(H + (size_t)m * DM))[lane + 64 * j] = b[j]; }
;         if (gnext) {
;             const float r2 = 1.f / sqrtf(wave_sum_fast(s2) * (1.f / DM) + EPS);
;             u32x2* o8 = (u32x2*)(XN + (size_t)m * DM) + lane;
; #pragma unroll
;             for (int j = 0; j < 4; ++j) { u32x2 w; w.x = pk2(b[j].x * r2 * gn[j].x, b[j].y * r2 * gn[j].y); w.y = pk2(b[j].z * r2 * gn[j].z, b[j].w * r2 * gn[j].w); o8[64 * j] = w; }
;         }
;         if (more) {
; #pragma unroll
;             for (int j = 0; j < 4; ++j) { f[j] = f2[j]; b[j] = b2[j]; } }
	v_mul_f32_e32 v96, v33, v33
	v_mul_f32_e32 v98, v35, v35
	v_fmac_f32_e32 v96, v32, v32
	v_fmac_f32_e32 v98, v34, v34
	v_add_f32_e32 v96, v96, v98
	v_mul_f32_e32 v97, v37, v37
	v_mul_f32_e32 v98, v39, v39
	v_fmac_f32_e32 v97, v36, v36
	v_fmac_f32_e32 v98, v38, v38
	v_add_f32_e32 v97, v97, v98
	v_add_f32_e32 v96, v97, v96
	v_mul_f32_e32 v97, v41, v41
	v_mul_f32_e32 v98, v43, v43
	v_fmac_f32_e32 v97, v40, v40
	v_fmac_f32_e32 v98, v42, v42
	v_add_f32_e32 v97, v97, v98
	v_add_f32_e32 v96, v97, v96
	v_mul_f32_e32 v97, v45, v45
	v_mul_f32_e32 v98, v47, v47
	v_fmac_f32_e32 v97, v44, v44
	v_fmac_f32_e32 v98, v46, v46
	v_add_f32_e32 v97, v97, v98
	v_add_f32_e32 v96, v97, v96
	s_nop 1
	v_add_f32_dpp v96, v96, v96 quad_perm:[1,0,3,2] row_mask:0xf bank_mask:0xf bound_ctrl:1
	s_nop 1
	v_add_f32_dpp v96, v96, v96 quad_perm:[2,3,0,1] row_mask:0xf bank_mask:0xf bound_ctrl:1
	s_nop 1
	v_add_f32_dpp v96, v96, v96 row_half_mirror row_mask:0xf bank_mask:0xf bound_ctrl:1
	s_nop 1
	v_add_f32_dpp v96, v96, v96 row_mirror row_mask:0xf bank_mask:0xf bound_ctrl:1
	v_mov_b32_e32 v97, v96
	s_nop 1
	v_permlane16_swap_b32_e32 v96, v97
	v_add_f32_e32 v96, v96, v97
	v_mov_b32_e32 v97, v96
	s_nop 1
	v_permlane32_swap_b32_e32 v96, v97
	v_add_f32_e32 v96, v96, v97
	v_fmamk_f32 v96, v96, 0x3a800000, v146
	v_mul_f32_e32 v97, 0x4f800000, v96
	v_cmp_gt_f32_e32 vcc, s33, v96
	s_nop 1
	v_cndmask_b32_e32 v96, v96, v97, vcc
	v_sqrt_f32_e32 v97, v96
	s_nop 0
	v_add_u32_e32 v98, -1, v97
	v_fma_f32 v99, -v98, v97, v96
	v_cmp_ge_f32_e64 s[4:5], 0, v99
	v_add_u32_e32 v99, 1, v97
	s_nop 0
	v_cndmask_b32_e64 v98, v97, v98, s[4:5]
	v_fma_f32 v97, -v99, v97, v96
	v_cmp_lt_f32_e64 s[4:5], 0, v97
	s_nop 1
	v_cndmask_b32_e64 v97, v98, v99, s[4:5]
	v_mul_f32_e32 v98, 0x37800000, v97
	v_cndmask_b32_e32 v97, v97, v98, vcc
	v_cmp_class_f32_e32 vcc, v96, v147
	s_nop 1
	v_cndmask_b32_e32 v96, v97, v96, vcc
	v_div_scale_f32 v97, s[4:5], v96, v96, 0.5
	v_rcp_f32_e32 v98, v97
	s_nop 0
	v_fma_f32 v99, -v97, v98, 1.0
	v_fmac_f32_e32 v98, v99, v98
	v_div_scale_f32 v99, vcc, 0.5, v96, 0.5
	v_mul_f32_e32 v100, v99, v98
	v_fma_f32 v101, -v97, v100, v99
	v_fmac_f32_e32 v100, v101, v98
	v_fma_f32 v97, -v97, v100, v99
	v_div_fmas_f32 v97, v97, v98, v100
	v_div_fixup_f32 v96, v97, v96, 0.5
	v_mul_f32_e32 v32, v32, v96
	v_mul_f32_e32 v33, v33, v96
	v_mul_f32_e32 v34, v34, v96
	v_mul_f32_e32 v35, v35, v96
	v_mul_f32_e32 v36, v36, v96
	v_mul_f32_e32 v37, v37, v96
	v_mul_f32_e32 v38, v38, v96
	v_mul_f32_e32 v39, v39, v96
	v_mul_f32_e32 v40, v40, v96
	v_mul_f32_e32 v41, v41, v96
	v_mul_f32_e32 v42, v42, v96
	v_mul_f32_e32 v43, v43, v96
	v_mul_f32_e32 v44, v44, v96
	v_mul_f32_e32 v45, v45, v96
	v_mul_f32_e32 v46, v46, v96
	v_mul_f32_e32 v47, v47, v96
	v_fmac_f32_e32 v48, v112, v32
	v_fmac_f32_e32 v49, v113, v33
	v_fmac_f32_e32 v50, v114, v34
	v_fmac_f32_e32 v51, v115, v35
	v_fmac_f32_e32 v52, v116, v36
	v_fmac_f32_e32 v53, v117, v37
	v_fmac_f32_e32 v54, v118, v38
	v_fmac_f32_e32 v55, v119, v39
	v_fmac_f32_e32 v56, v120, v40
	v_fmac_f32_e32 v57, v121, v41
	v_fmac_f32_e32 v58, v122, v42
	v_fmac_f32_e32 v59, v123, v43
	v_fmac_f32_e32 v60, v124, v44
	v_fmac_f32_e32 v61, v125, v45
	v_fmac_f32_e32 v62, v126, v46
	v_fmac_f32_e32 v63, v127, v47
	global_store_dwordx4 v144, v[48:51], s[40:41] offset:0
	global_store_dwordx4 v144, v[52:55], s[40:41] offset:1024
	global_store_dwordx4 v144, v[56:59], s[40:41] offset:2048
	global_store_dwordx4 v144, v[60:63], s[40:41] offset:3072
	v_mul_f32_e32 v96, v49, v49
	v_mul_f32_e32 v98, v51, v51
	v_fmac_f32_e32 v96, v48, v48
	v_fmac_f32_e32 v98, v50, v50
	v_add_f32_e32 v96, v96, v98
	v_mul_f32_e32 v97, v53, v53
	v_mul_f32_e32 v98, v55, v55
	v_fmac_f32_e32 v97, v52, v52
	v_fmac_f32_e32 v98, v54, v54
	v_add_f32_e32 v97, v97, v98
	v_add_f32_e32 v96, v97, v96
	v_mul_f32_e32 v97, v57, v57
	v_mul_f32_e32 v98, v59, v59
	v_fmac_f32_e32 v97, v56, v56
	v_fmac_f32_e32 v98, v58, v58
	v_add_f32_e32 v97, v97, v98
	v_add_f32_e32 v96, v97, v96
	v_mul_f32_e32 v97, v61, v61
	v_mul_f32_e32 v98, v63, v63
	v_fmac_f32_e32 v97, v60, v60
	v_fmac_f32_e32 v98, v62, v62
	v_add_f32_e32 v97, v97, v98
	v_add_f32_e32 v96, v97, v96
	s_nop 1
	v_add_f32_dpp v96, v96, v96 quad_perm:[1,0,3,2] row_mask:0xf bank_mask:0xf bound_ctrl:1
	s_nop 1
	v_add_f32_dpp v96, v96, v96 quad_perm:[2,3,0,1] row_mask:0xf bank_mask:0xf bound_ctrl:1
	s_nop 1
	v_add_f32_dpp v96, v96, v96 row_half_mirror row_mask:0xf bank_mask:0xf bound_ctrl:1
	s_nop 1
	v_add_f32_dpp v96, v96, v96 row_mirror row_mask:0xf bank_mask:0xf bound_ctrl:1
	v_mov_b32_e32 v97, v96
	s_nop 1
	v_permlane16_swap_b32_e32 v96, v97
	v_add_f32_e32 v96, v96, v97
	v_mov_b32_e32 v97, v96
	s_nop 1
	v_permlane32_swap_b32_e32 v96, v97
	v_add_f32_e32 v96, v96, v97
	v_fmamk_f32 v96, v96, 0x3a800000, v146
	v_mul_f32_e32 v97, 0x4f800000, v96
	v_cmp_gt_f32_e32 vcc, s33, v96
	s_nop 1
	v_cndmask_b32_e32 v96, v96, v97, vcc
	v_sqrt_f32_e32 v97, v96
	s_nop 0
	v_add_u32_e32 v98, -1, v97
	v_fma_f32 v99, -v98, v97, v96
	v_cmp_ge_f32_e64 s[4:5], 0, v99
	v_add_u32_e32 v99, 1, v97
	s_nop 0
	v_cndmask_b32_e64 v98, v97, v98, s[4:5]
	v_fma_f32 v97, -v99, v97, v96
	v_cmp_lt_f32_e64 s[4:5], 0, v97
	s_nop 1
	v_cndmask_b32_e64 v97, v98, v99, s[4:5]
	v_mul_f32_e32 v98, 0x37800000, v97
	v_cndmask_b32_e32 v97, v97, v98, vcc
	v_cmp_class_f32_e32 vcc, v96, v147
	s_nop 1
	v_cndmask_b32_e32 v96, v97, v96, vcc
	v_div_scale_f32 v97, s[4:5], v96, v96, 1.0
	v_rcp_f32_e32 v98, v97
	s_nop 0
	v_fma_f32 v99, -v97, v98, 1.0
	v_fmac_f32_e32 v98, v99, v98
	v_div_scale_f32 v99, vcc, 1.0, v96, 1.0
	v_mul_f32_e32 v100, v99, v98
	v_fma_f32 v101, -v97, v100, v99
	v_fmac_f32_e32 v100, v101, v98
	v_fma_f32 v97, -v97, v100, v99
; __device__ __forceinline__ unsigned pk2(float lo, float hi) { f32x2 v = {lo, hi}; bf16x2_t b = __builtin_convertvector(v, bf16x2_t); return __builtin_bit_cast(unsigned, b); }
; __device__ __forceinline__ void phase_rowpass(const Ctx& p, const float* F, int base_is_x, float alpha, const float* gpost, const float* gnext, bf16_t* XN, const float* PART, int nsplit) {
;     ...
;     for (int m = gw; m < MR; m += NGW) {
;         const bool more = m + NGW < MR;
;         if (more) loadrow(m + NGW, f2, b2);
;         float s = 0.f;
; #pragma unroll
;         for (int j = 0; j < 4; ++j) s += (f[j].x * f[j].x + f[j].y * f[j].y) + (f[j].z * f[j].z + f[j].w * f[j].w);
;         const float rs = alpha / sqrtf(wave_sum_fast(s) * (1.f / DM) + EPS);
;         float s2 = 0.f;
; #pragma unroll
;         for (int j = 0; j < 4; ++j) { b[j] = b[j] + f[j] * rs * gp[j]; s2 += (b[j].x * b[j].x + b[j].y * b[j].y) + (b[j].z * b[j].z + b[j].w * b[j].w);
;             ((f32x4*)(H + (size_t)m * DM))[lane + 64 * j] = b[j]; }
;         if (gnext) {
;             const float r2 = 1.f / sqrtf(wave_sum_fast(s2) * (1.f / DM) + EPS);
;             u32x2* o8 = (u32x2*)(XN + (size_t)m * DM) + lane;
; #pragma unroll
;             for (int j = 0; j < 4; ++j) { u32x2 w; w.x = pk2(b[j].x * r2 * gn[j].x, b[j].y * r2 * gn[j].y); w.y = pk2(b[j].z * r2 * gn[j].z, b[j].w * r2 * gn[j].w); o8[64 * j] = w; }
;         }
;         if (more) {
; #pragma unroll
;             for (int j = 0; j < 4; ++j) { f[j] = f2[j]; b[j] = b2[j]; } }
	v_div_fmas_f32 v97, v97, v98, v100
	v_div_fixup_f32 v96, v97, v96, 1.0
	v_mul_f32_e32 v32, v48, v96
	v_mul_f32_e32 v33, v49, v96
	v_mul_f32_e32 v34, v50, v96
	v_mul_f32_e32 v35, v51, v96
	v_mul_f32_e32 v36, v52, v96
	v_mul_f32_e32 v37, v53, v96
	v_mul_f32_e32 v38, v54, v96
	v_mul_f32_e32 v39, v55, v96
	v_mul_f32_e32 v40, v56, v96
	v_mul_f32_e32 v41, v57, v96
	v_mul_f32_e32 v42, v58, v96
	v_mul_f32_e32 v43, v59, v96
	v_mul_f32_e32 v44, v60, v96
	v_mul_f32_e32 v45, v61, v96
	v_mul_f32_e32 v46, v62, v96
	v_mul_f32_e32 v47, v63, v96
	v_mul_f32_e32 v32, v128, v32
	v_mul_f32_e32 v33, v129, v33
	v_mul_f32_e32 v34, v130, v34
	v_mul_f32_e32 v35, v131, v35
	v_mul_f32_e32 v36, v132, v36
	v_mul_f32_e32 v37, v133, v37
	v_mul_f32_e32 v38, v134, v38
	v_mul_f32_e32 v39, v135, v39
	v_mul_f32_e32 v40, v136, v40
	v_mul_f32_e32 v41, v137, v41
	v_mul_f32_e32 v42, v138, v42
	v_mul_f32_e32 v43, v139, v43
	v_mul_f32_e32 v44, v140, v44
	v_mul_f32_e32 v45, v141, v45
	v_mul_f32_e32 v46, v142, v46
	v_mul_f32_e32 v47, v143, v47
	v_cvt_pk_bf16_f32 v148, v32, v33
	v_cvt_pk_bf16_f32 v149, v34, v35
	global_store_dwordx2 v145, v[148:149], s[42:43] offset:0
	v_cvt_pk_bf16_f32 v150, v36, v37
	v_cvt_pk_bf16_f32 v151, v38, v39
	global_store_dwordx2 v145, v[150:151], s[42:43] offset:512
	v_cvt_pk_bf16_f32 v152, v40, v41
	v_cvt_pk_bf16_f32 v153, v42, v43
	global_store_dwordx2 v145, v[152:153], s[42:43] offset:1024
	v_cvt_pk_bf16_f32 v154, v44, v45
	v_cvt_pk_bf16_f32 v155, v46, v47
	global_store_dwordx2 v145, v[154:155], s[42:43] offset:1536
	s_add_u32 s40, s40, 0x8000
	s_addc_u32 s41, s41, 0
	s_add_u32 s42, s42, 0x4000
	s_addc_u32 s43, s43, 0
	global_load_dwordx4 v[32:35], v144, s[24:25] offset:0
	global_load_dwordx4 v[36:39], v144, s[24:25] offset:1024
	global_load_dwordx4 v[40:43], v144, s[24:25] offset:2048
	global_load_dwordx4 v[44:47], v144, s[24:25] offset:3072
	global_load_dwordx4 v[48:51], v144, s[26:27] offset:0
	global_load_dwordx4 v[52:55], v144, s[26:27] offset:1024
	global_load_dwordx4 v[56:59], v144, s[26:27] offset:2048
	global_load_dwordx4 v[60:63], v144, s[26:27] offset:3072
	s_add_u32 s24, s24, 0x8000
	s_addc_u32 s25, s25, 0
	s_add_u32 s26, s26, 0x8000
	s_addc_u32 s27, s27, 0
	s_waitcnt vmcnt(32)
	v_mul_f32_e32 v96, v65, v65
	v_mul_f32_e32 v98, v67, v67
	v_fmac_f32_e32 v96, v64, v64
	v_fmac_f32_e32 v98, v66, v66
	v_add_f32_e32 v96, v96, v98
	v_mul_f32_e32 v97, v69, v69
	v_mul_f32_e32 v98, v71, v71
	v_fmac_f32_e32 v97, v68, v68
	v_fmac_f32_e32 v98, v70, v70
	v_add_f32_e32 v97, v97, v98
	v_add_f32_e32 v96, v97, v96
	v_mul_f32_e32 v97, v73, v73
	v_mul_f32_e32 v98, v75, v75
	v_fmac_f32_e32 v97, v72, v72
	v_fmac_f32_e32 v98, v74, v74
	v_add_f32_e32 v97, v97, v98
	v_add_f32_e32 v96, v97, v96
	v_mul_f32_e32 v97, v77, v77
	v_mul_f32_e32 v98, v79, v79
	v_fmac_f32_e32 v97, v76, v76
	v_fmac_f32_e32 v98, v78, v78
	v_add_f32_e32 v97, v97, v98
	v_add_f32_e32 v96, v97, v96
	s_nop 1
	v_add_f32_dpp v96, v96, v96 quad_perm:[1,0,3,2] row_mask:0xf bank_mask:0xf bound_ctrl:1
	s_nop 1
	v_add_f32_dpp v96, v96, v96 quad_perm:[2,3,0,1] row_mask:0xf bank_mask:0xf bound_ctrl:1
	s_nop 1
	v_add_f32_dpp v96, v96, v96 row_half_mirror row_mask:0xf bank_mask:0xf bound_ctrl:1
	s_nop 1
	v_add_f32_dpp v96, v96, v96 row_mirror row_mask:0xf bank_mask:0xf bound_ctrl:1
	v_mov_b32_e32 v97, v96
	s_nop 1
	v_permlane16_swap_b32_e32 v96, v97
	v_add_f32_e32 v96, v96, v97
	v_mov_b32_e32 v97, v96
	s_nop 1
	v_permlane32_swap_b32_e32 v96, v97
	v_add_f32_e32 v96, v96, v97
	v_fmamk_f32 v96, v96, 0x3a800000, v146
	v_mul_f32_e32 v97, 0x4f800000, v96
	v_cmp_gt_f32_e32 vcc, s33, v96
	s_nop 1
	v_cndmask_b32_e32 v96, v96, v97, vcc
	v_sqrt_f32_e32 v97, v96
	s_nop 0
	v_add_u32_e32 v98, -1, v97
	v_fma_f32 v99, -v98, v97, v96
	v_cmp_ge_f32_e64 s[4:5], 0, v99
	v_add_u32_e32 v99, 1, v97
	s_nop 0
	v_cndmask_b32_e64 v98, v97, v98, s[4:5]
	v_fma_f32 v97, -v99, v97, v96
	v_cmp_lt_f32_e64 s[4:5], 0, v97
	s_nop 1
	v_cndmask_b32_e64 v97, v98, v99, s[4:5]
	v_mul_f32_e32 v98, 0x37800000, v97
	v_cndmask_b32_e32 v97, v97, v98, vcc
	v_cmp_class_f32_e32 vcc, v96, v147
	s_nop 1
	v_cndmask_b32_e32 v96, v97, v96, vcc
	v_div_scale_f32 v97, s[4:5], v96, v96, 0.5
	v_rcp_f32_e32 v98, v97
	s_nop 0
	v_fma_f32 v99, -v97, v98, 1.0
	v_fmac_f32_e32 v98, v99, v98
	v_div_scale_f32 v99, vcc, 0.5, v96, 0.5
	v_mul_f32_e32 v100, v99, v98
	v_fma_f32 v101, -v97, v100, v99
	v_fmac_f32_e32 v100, v101, v98
	v_fma_f32 v97, -v97, v100, v99
	v_div_fmas_f32 v97, v97, v98, v100
	v_div_fixup_f32 v96, v97, v96, 0.5
	v_mul_f32_e32 v64, v64, v96
	v_mul_f32_e32 v65, v65, v96
	v_mul_f32_e32 v66, v66, v96
	v_mul_f32_e32 v67, v67, v96
	v_mul_f32_e32 v68, v68, v96
	v_mul_f32_e32 v69, v69, v96
	v_mul_f32_e32 v70, v70, v96
	v_mul_f32_e32 v71, v71, v96
	v_mul_f32_e32 v72, v72, v96
	v_mul_f32_e32 v73, v73, v96
	v_mul_f32_e32 v74, v74, v96
	v_mul_f32_e32 v75, v75, v96
	v_mul_f32_e32 v76, v76, v96
	v_mul_f32_e32 v77, v77, v96
	v_mul_f32_e32 v78, v78, v96
	v_mul_f32_e32 v79, v79, v96
	v_fmac_f32_e32 v80, v112, v64
	v_fmac_f32_e32 v81, v113, v65
	v_fmac_f32_e32 v82, v114, v66
	v_fmac_f32_e32 v83, v115, v67
	v_fmac_f32_e32 v84, v116, v68
	v_fmac_f32_e32 v85, v117, v69
	v_fmac_f32_e32 v86, v118, v70
	v_fmac_f32_e32 v87, v119, v71
	v_fmac_f32_e32 v88, v120, v72
	v_fmac_f32_e32 v89, v121, v73
	v_fmac_f32_e32 v90, v122, v74
	v_fmac_f32_e32 v91, v123, v75
	v_fmac_f32_e32 v92, v124, v76
	v_fmac_f32_e32 v93, v125, v77
	v_fmac_f32_e32 v94, v126, v78
	v_fmac_f32_e32 v95, v127, v79
	global_store_dwordx4 v144, v[80:83], s[40:41] offset:0
	global_store_dwordx4 v144, v[84:87], s[40:41] offset:1024
	global_store_dwordx4 v144, v[88:91], s[40:41] offset:2048
	global_store_dwordx4 v144, v[92:95], s[40:41] offset:3072
; __device__ __forceinline__ unsigned pk2(float lo, float hi) { f32x2 v = {lo, hi}; bf16x2_t b = __builtin_convertvector(v, bf16x2_t); return __builtin_bit_cast(unsigned, b); }
; __device__ __forceinline__ void phase_rowpass(const Ctx& p, const float* F, int base_is_x, float alpha, const float* gpost, const float* gnext, bf16_t* XN, const float* PART, int nsplit) {
;     ...
;     for (int m = gw; m < MR; m += NGW) {
;         const bool more = m + NGW < MR;
;         if (more) loadrow(m + NGW, f2, b2);
;         float s = 0.f;
; #pragma unroll
;         for (int j = 0; j < 4; ++j) s += (f[j].x * f[j].x + f[j].y * f[j].y) + (f[j].z * f[j].z + f[j].w * f[j].w);
;         const float rs = alpha / sqrtf(wave_sum_fast(s) * (1.f / DM) + EPS);
;         float s2 = 0.f;
; #pragma unroll
;         for (int j = 0; j < 4; ++j) { b[j] = b[j] + f[j] * rs * gp[j]; s2 += (b[j].x * b[j].x + b[j].y * b[j].y) + (b[j].z * b[j].z + b[j].w * b[j].w);
;             ((f32x4*)(H + (size_t)m * DM))[lane + 64 * j] = b[j]; }
;         if (gnext) {
;             const float r2 = 1.f / sqrtf(wave_sum_fast(s2) * (1.f / DM) + EPS);
;             u32x2* o8 = (u32x2*)(XN + (size_t)m * DM) + lane;
; #pragma unroll
;             for (int j = 0; j < 4; ++j) { u32x2 w; w.x = pk2(b[j].x * r2 * gn[j].x, b[j].y * r2 * gn[j].y); w.y = pk2(b[j].z * r2 * gn[j].z, b[j].w * r2 * gn[j].w); o8[64 * j] = w; }
;         }
;         if (more) {
; #pragma unroll
;             for (int j = 0; j < 4; ++j) { f[j] = f2[j]; b[j] = b2[j]; } }
	v_mul_f32_e32 v96, v81, v81
	v_mul_f32_e32 v98, v83, v83
	v_fmac_f32_e32 v96, v80, v80
	v_fmac_f32_e32 v98, v82, v82
	v_add_f32_e32 v96, v96, v98
	v_mul_f32_e32 v97, v85, v85
	v_mul_f32_e32 v98, v87, v87
	v_fmac_f32_e32 v97, v84, v84
	v_fmac_f32_e32 v98, v86, v86
	v_add_f32_e32 v97, v97, v98
	v_add_f32_e32 v96, v97, v96
	v_mul_f32_e32 v97, v89, v89
	v_mul_f32_e32 v98, v91, v91
	v_fmac_f32_e32 v97, v88, v88
	v_fmac_f32_e32 v98, v90, v90
	v_add_f32_e32 v97, v97, v98
	v_add_f32_e32 v96, v97, v96
	v_mul_f32_e32 v97, v93, v93
	v_mul_f32_e32 v98, v95, v95
	v_fmac_f32_e32 v97, v92, v92
	v_fmac_f32_e32 v98, v94, v94
	v_add_f32_e32 v97, v97, v98
	v_add_f32_e32 v96, v97, v96
	s_nop 1
	v_add_f32_dpp v96, v96, v96 quad_perm:[1,0,3,2] row_mask:0xf bank_mask:0xf bound_ctrl:1
	s_nop 1
	v_add_f32_dpp v96, v96, v96 quad_perm:[2,3,0,1] row_mask:0xf bank_mask:0xf bound_ctrl:1
	s_nop 1
	v_add_f32_dpp v96, v96, v96 row_half_mirror row_mask:0xf bank_mask:0xf bound_ctrl:1
	s_nop 1
	v_add_f32_dpp v96, v96, v96 row_mirror row_mask:0xf bank_mask:0xf bound_ctrl:1
	v_mov_b32_e32 v97, v96
	s_nop 1
	v_permlane16_swap_b32_e32 v96, v97
	v_add_f32_e32 v96, v96, v97
	v_mov_b32_e32 v97, v96
	s_nop 1
	v_permlane32_swap_b32_e32 v96, v97
	v_add_f32_e32 v96, v96, v97
	v_fmamk_f32 v96, v96, 0x3a800000, v146
	v_mul_f32_e32 v97, 0x4f800000, v96
	v_cmp_gt_f32_e32 vcc, s33, v96
	s_nop 1
	v_cndmask_b32_e32 v96, v96, v97, vcc
	v_sqrt_f32_e32 v97, v96
	s_nop 0
	v_add_u32_e32 v98, -1, v97
	v_fma_f32 v99, -v98, v97, v96
	v_cmp_ge_f32_e64 s[4:5], 0, v99
	v_add_u32_e32 v99, 1, v97
	s_nop 0
	v_cndmask_b32_e64 v98, v97, v98, s[4:5]
	v_fma_f32 v97, -v99, v97, v96
	v_cmp_lt_f32_e64 s[4:5], 0, v97
	s_nop 1
	v_cndmask_b32_e64 v97, v98, v99, s[4:5]
	v_mul_f32_e32 v98, 0x37800000, v97
	v_cndmask_b32_e32 v97, v97, v98, vcc
	v_cmp_class_f32_e32 vcc, v96, v147
	s_nop 1
	v_cndmask_b32_e32 v96, v97, v96, vcc
	v_div_scale_f32 v97, s[4:5], v96, v96, 1.0
	v_rcp_f32_e32 v98, v97
	s_nop 0
	v_fma_f32 v99, -v97, v98, 1.0
	v_fmac_f32_e32 v98, v99, v98
	v_div_scale_f32 v99, vcc, 1.0, v96, 1.0
	v_mul_f32_e32 v100, v99, v98
	v_fma_f32 v101, -v97, v100, v99
	v_fmac_f32_e32 v100, v101, v98
	v_fma_f32 v97, -v97, v100, v99
	v_div_fmas_f32 v97, v97, v98, v100
	v_div_fixup_f32 v96, v97, v96, 1.0
	v_mul_f32_e32 v64, v80, v96
	v_mul_f32_e32 v65, v81, v96
	v_mul_f32_e32 v66, v82, v96
	v_mul_f32_e32 v67, v83, v96
	v_mul_f32_e32 v68, v84, v96
	v_mul_f32_e32 v69, v85, v96
	v_mul_f32_e32 v70, v86, v96
	v_mul_f32_e32 v71, v87, v96
	v_mul_f32_e32 v72, v88, v96
	v_mul_f32_e32 v73, v89, v96
	v_mul_f32_e32 v74, v90, v96
	v_mul_f32_e32 v75, v91, v96
	v_mul_f32_e32 v76, v92, v96
	v_mul_f32_e32 v77, v93, v96
	v_mul_f32_e32 v78, v94, v96
	v_mul_f32_e32 v79, v95, v96
	v_mul_f32_e32 v64, v128, v64
	v_mul_f32_e32 v65, v129, v65
	v_mul_f32_e32 v66, v130, v66
	v_mul_f32_e32 v67, v131, v67
	v_mul_f32_e32 v68, v132, v68
	v_mul_f32_e32 v69, v133, v69
	v_mul_f32_e32 v70, v134, v70
	v_mul_f32_e32 v71, v135, v71
	v_mul_f32_e32 v72, v136, v72
	v_mul_f32_e32 v73, v137, v73
	v_mul_f32_e32 v74, v138, v74
	v_mul_f32_e32 v75, v139, v75
	v_mul_f32_e32 v76, v140, v76
	v_mul_f32_e32 v77, v141, v77
	v_mul_f32_e32 v78, v142, v78
	v_mul_f32_e32 v79, v143, v79
	v_cvt_pk_bf16_f32 v148, v64, v65
	v_cvt_pk_bf16_f32 v149, v66, v67
	global_store_dwordx2 v145, v[148:149], s[42:43] offset:0
	v_cvt_pk_bf16_f32 v150, v68, v69
	v_cvt_pk_bf16_f32 v151, v70, v71
	global_store_dwordx2 v145, v[150:151], s[42:43] offset:512
	v_cvt_pk_bf16_f32 v152, v72, v73
	v_cvt_pk_bf16_f32 v153, v74, v75
	global_store_dwordx2 v145, v[152:153], s[42:43] offset:1024
	v_cvt_pk_bf16_f32 v154, v76, v77
	v_cvt_pk_bf16_f32 v155, v78, v79
	global_store_dwordx2 v145, v[154:155], s[42:43] offset:1536
	s_add_u32 s40, s40, 0x8000
	s_addc_u32 s41, s41, 0
	s_add_u32 s42, s42, 0x4000
	s_addc_u32 s43, s43, 0
	global_load_dwordx4 v[64:67], v144, s[24:25] offset:0
	global_load_dwordx4 v[68:71], v144, s[24:25] offset:1024
	global_load_dwordx4 v[72:75], v144, s[24:25] offset:2048
	global_load_dwordx4 v[76:79], v144, s[24:25] offset:3072
	global_load_dwordx4 v[80:83], v144, s[26:27] offset:0
	global_load_dwordx4 v[84:87], v144, s[26:27] offset:1024
	global_load_dwordx4 v[88:91], v144, s[26:27] offset:2048
	global_load_dwordx4 v[92:95], v144, s[26:27] offset:3072
	s_add_u32 s24, s24, 0x8000
	s_addc_u32 s25, s25, 0
	s_add_u32 s26, s26, 0x8000
	s_addc_u32 s27, s27, 0
	s_waitcnt vmcnt(32)
; __device__ __forceinline__ unsigned pk2(float lo, float hi) { f32x2 v = {lo, hi}; bf16x2_t b = __builtin_convertvector(v, bf16x2_t); return __builtin_bit_cast(unsigned, b); }
; __device__ __forceinline__ void phase_rowpass(const Ctx& p, const float* F, int base_is_x, float alpha, const float* gpost, const float* gnext, bf16_t* XN, const float* PART, int nsplit) {
;     ...
;     for (int m = gw; m < MR; m += NGW) {
;         const bool more = m + NGW < MR;
;         if (more) loadrow(m + NGW, f2, b2);
;         float s = 0.f;
; #pragma unroll
;         for (int j = 0; j < 4; ++j) s += (f[j].x * f[j].x + f[j].y * f[j].y) + (f[j].z * f[j].z + f[j].w * f[j].w);
;         const float rs = alpha / sqrtf(wave_sum_fast(s) * (1.f / DM) + EPS);
;         float s2 = 0.f;
; #pragma unroll
;         for (int j = 0; j < 4; ++j) { b[j] = b[j] + f[j] * rs * gp[j]; s2 += (b[j].x * b[j].x + b[j].y * b[j].y) + (b[j].z * b[j].z + b[j].w * b[j].w);
;             ((f32x4*)(H + (size_t)m * DM))[lane + 64 * j] = b[j]; }
;         if (gnext) {
;             const float r2 = 1.f / sqrtf(wave_sum_fast(s2) * (1.f / DM) + EPS);
;             u32x2* o8 = (u32x2*)(XN + (size_t)m * DM) + lane;
; #pragma unroll
;             for (int j = 0; j < 4; ++j) { u32x2 w; w.x = pk2(b[j].x * r2 * gn[j].x, b[j].y * r2 * gn[j].y); w.y = pk2(b[j].z * r2 * gn[j].z, b[j].w * r2 * gn[j].w); o8[64 * j] = w; }
;         }
;         if (more) {
; #pragma unroll
;             for (int j = 0; j < 4; ++j) { f[j] = f2[j]; b[j] = b2[j]; } }
	v_mul_f32_e32 v96, v1, v1
	v_mul_f32_e32 v98, v3, v3
	v_fmac_f32_e32 v96, v0, v0
	v_fmac_f32_e32 v98, v2, v2
	v_add_f32_e32 v96, v96, v98
	v_mul_f32_e32 v97, v5, v5
	v_mul_f32_e32 v98, v7, v7
	v_fmac_f32_e32 v97, v4, v4
	v_fmac_f32_e32 v98, v6, v6
	v_add_f32_e32 v97, v97, v98
	v_add_f32_e32 v96, v97, v96
	v_mul_f32_e32 v97, v9, v9
	v_mul_f32_e32 v98, v11, v11
	v_fmac_f32_e32 v97, v8, v8
	v_fmac_f32_e32 v98, v10, v10
	v_add_f32_e32 v97, v97, v98
	v_add_f32_e32 v96, v97, v96
	v_mul_f32_e32 v97, v13, v13
	v_mul_f32_e32 v98, v15, v15
	v_fmac_f32_e32 v97, v12, v12
	v_fmac_f32_e32 v98, v14, v14
	v_add_f32_e32 v97, v97, v98
	v_add_f32_e32 v96, v97, v96
	s_nop 1
	v_add_f32_dpp v96, v96, v96 quad_perm:[1,0,3,2] row_mask:0xf bank_mask:0xf bound_ctrl:1
	s_nop 1
	v_add_f32_dpp v96, v96, v96 quad_perm:[2,3,0,1] row_mask:0xf bank_mask:0xf bound_ctrl:1
	s_nop 1
	v_add_f32_dpp v96, v96, v96 row_half_mirror row_mask:0xf bank_mask:0xf bound_ctrl:1
	s_nop 1
	v_add_f32_dpp v96, v96, v96 row_mirror row_mask:0xf bank_mask:0xf bound_ctrl:1
	v_mov_b32_e32 v97, v96
	s_nop 1
	v_permlane16_swap_b32_e32 v96, v97
	v_add_f32_e32 v96, v96, v97
	v_mov_b32_e32 v97, v96
	s_nop 1
	v_permlane32_swap_b32_e32 v96, v97
	v_add_f32_e32 v96, v96, v97
	v_fmamk_f32 v96, v96, 0x3a800000, v146
	v_mul_f32_e32 v97, 0x4f800000, v96
	v_cmp_gt_f32_e32 vcc, s33, v96
	s_nop 1
	v_cndmask_b32_e32 v96, v96, v97, vcc
	v_sqrt_f32_e32 v97, v96
	s_nop 0
	v_add_u32_e32 v98, -1, v97
	v_fma_f32 v99, -v98, v97, v96
	v_cmp_ge_f32_e64 s[4:5], 0, v99
	v_add_u32_e32 v99, 1, v97
	s_nop 0
	v_cndmask_b32_e64 v98, v97, v98, s[4:5]
	v_fma_f32 v97, -v99, v97, v96
	v_cmp_lt_f32_e64 s[4:5], 0, v97
	s_nop 1
	v_cndmask_b32_e64 v97, v98, v99, s[4:5]
	v_mul_f32_e32 v98, 0x37800000, v97
	v_cndmask_b32_e32 v97, v97, v98, vcc
	v_cmp_class_f32_e32 vcc, v96, v147
	s_nop 1
	v_cndmask_b32_e32 v96, v97, v96, vcc
	v_div_scale_f32 v97, s[4:5], v96, v96, 0.5
	v_rcp_f32_e32 v98, v97
	s_nop 0
	v_fma_f32 v99, -v97, v98, 1.0
	v_fmac_f32_e32 v98, v99, v98
	v_div_scale_f32 v99, vcc, 0.5, v96, 0.5
	v_mul_f32_e32 v100, v99, v98
	v_fma_f32 v101, -v97, v100, v99
	v_fmac_f32_e32 v100, v101, v98
	v_fma_f32 v97, -v97, v100, v99
	v_div_fmas_f32 v97, v97, v98, v100
	v_div_fixup_f32 v96, v97, v96, 0.5
	v_mul_f32_e32 v0, v0, v96
	v_mul_f32_e32 v1, v1, v96
	v_mul_f32_e32 v2, v2, v96
	v_mul_f32_e32 v3, v3, v96
	v_mul_f32_e32 v4, v4, v96
	v_mul_f32_e32 v5, v5, v96
	v_mul_f32_e32 v6, v6, v96
	v_mul_f32_e32 v7, v7, v96
	v_mul_f32_e32 v8, v8, v96
	v_mul_f32_e32 v9, v9, v96
	v_mul_f32_e32 v10, v10, v96
	v_mul_f32_e32 v11, v11, v96
	v_mul_f32_e32 v12, v12, v96
	v_mul_f32_e32 v13, v13, v96
	v_mul_f32_e32 v14, v14, v96
	v_mul_f32_e32 v15, v15, v96
	v_fmac_f32_e32 v16, v112, v0
	v_fmac_f32_e32 v17, v113, v1
	v_fmac_f32_e32 v18, v114, v2
	v_fmac_f32_e32 v19, v115, v3
	v_fmac_f32_e32 v20, v116, v4
	v_fmac_f32_e32 v21, v117, v5
	v_fmac_f32_e32 v22, v118, v6
	v_fmac_f32_e32 v23, v119, v7
	v_fmac_f32_e32 v24, v120, v8
	v_fmac_f32_e32 v25, v121, v9
	v_fmac_f32_e32 v26, v122, v10
	v_fmac_f32_e32 v27, v123, v11
	v_fmac_f32_e32 v28, v124, v12
	v_fmac_f32_e32 v29, v125, v13
	v_fmac_f32_e32 v30, v126, v14
	v_fmac_f32_e32 v31, v127, v15
	global_store_dwordx4 v144, v[16:19], s[40:41] offset:0
	global_store_dwordx4 v144, v[20:23], s[40:41] offset:1024
	global_store_dwordx4 v144, v[24:27], s[40:41] offset:2048
	global_store_dwordx4 v144, v[28:31], s[40:41] offset:3072
	v_mul_f32_e32 v96, v17, v17
	v_mul_f32_e32 v98, v19, v19
	v_fmac_f32_e32 v96, v16, v16
	v_fmac_f32_e32 v98, v18, v18
	v_add_f32_e32 v96, v96, v98
	v_mul_f32_e32 v97, v21, v21
	v_mul_f32_e32 v98, v23, v23
	v_fmac_f32_e32 v97, v20, v20
	v_fmac_f32_e32 v98, v22, v22
	v_add_f32_e32 v97, v97, v98
	v_add_f32_e32 v96, v97, v96
	v_mul_f32_e32 v97, v25, v25
	v_mul_f32_e32 v98, v27, v27
	v_fmac_f32_e32 v97, v24, v24
	v_fmac_f32_e32 v98, v26, v26
	v_add_f32_e32 v97, v97, v98
	v_add_f32_e32 v96, v97, v96
	v_mul_f32_e32 v97, v29, v29
	v_mul_f32_e32 v98, v31, v31
	v_fmac_f32_e32 v97, v28, v28
	v_fmac_f32_e32 v98, v30, v30
	v_add_f32_e32 v97, v97, v98
	v_add_f32_e32 v96, v97, v96
	s_nop 1
	v_add_f32_dpp v96, v96, v96 quad_perm:[1,0,3,2] row_mask:0xf bank_mask:0xf bound_ctrl:1
	s_nop 1
	v_add_f32_dpp v96, v96, v96 quad_perm:[2,3,0,1] row_mask:0xf bank_mask:0xf bound_ctrl:1
	s_nop 1
	v_add_f32_dpp v96, v96, v96 row_half_mirror row_mask:0xf bank_mask:0xf bound_ctrl:1
	s_nop 1
	v_add_f32_dpp v96, v96, v96 row_mirror row_mask:0xf bank_mask:0xf bound_ctrl:1
	v_mov_b32_e32 v97, v96
	s_nop 1
	v_permlane16_swap_b32_e32 v96, v97
	v_add_f32_e32 v96, v96, v97
	v_mov_b32_e32 v97, v96
	s_nop 1
	v_permlane32_swap_b32_e32 v96, v97
	v_add_f32_e32 v96, v96, v97
	v_fmamk_f32 v96, v96, 0x3a800000, v146
	v_mul_f32_e32 v97, 0x4f800000, v96
	v_cmp_gt_f32_e32 vcc, s33, v96
	s_nop 1
	v_cndmask_b32_e32 v96, v96, v97, vcc
	v_sqrt_f32_e32 v97, v96
	s_nop 0
	v_add_u32_e32 v98, -1, v97
	v_fma_f32 v99, -v98, v97, v96
	v_cmp_ge_f32_e64 s[4:5], 0, v99
	v_add_u32_e32 v99, 1, v97
	s_nop 0
	v_cndmask_b32_e64 v98, v97, v98, s[4:5]
	v_fma_f32 v97, -v99, v97, v96
	v_cmp_lt_f32_e64 s[4:5], 0, v97
	s_nop 1
	v_cndmask_b32_e64 v97, v98, v99, s[4:5]
	v_mul_f32_e32 v98, 0x37800000, v97
	v_cndmask_b32_e32 v97, v97, v98, vcc
	v_cmp_class_f32_e32 vcc, v96, v147
	s_nop 1
	v_cndmask_b32_e32 v96, v97, v96, vcc
	v_div_scale_f32 v97, s[4:5], v96, v96, 1.0
	v_rcp_f32_e32 v98, v97
	s_nop 0
	v_fma_f32 v99, -v97, v98, 1.0
	v_fmac_f32_e32 v98, v99, v98
	v_div_scale_f32 v99, vcc, 1.0, v96, 1.0
	v_mul_f32_e32 v100, v99, v98
	v_fma_f32 v101, -v97, v100, v99
	v_fmac_f32_e32 v100, v101, v98
	v_fma_f32 v97, -v97, v100, v99
	v_div_fmas_f32 v97, v97, v98, v100
	v_div_fixup_f32 v96, v97, v96, 1.0
; __device__ __forceinline__ unsigned pk2(float lo, float hi) { f32x2 v = {lo, hi}; bf16x2_t b = __builtin_convertvector(v, bf16x2_t); return __builtin_bit_cast(unsigned, b); }
; __device__ __forceinline__ void phase_rowpass(const Ctx& p, const float* F, int base_is_x, float alpha, const float* gpost, const float* gnext, bf16_t* XN, const float* PART, int nsplit) {
;     ...
;     for (int m = gw; m < MR; m += NGW) {
;         const bool more = m + NGW < MR;
;         if (more) loadrow(m + NGW, f2, b2);
;         float s = 0.f;
; #pragma unroll
;         for (int j = 0; j < 4; ++j) s += (f[j].x * f[j].x + f[j].y * f[j].y) + (f[j].z * f[j].z + f[j].w * f[j].w);
;         const float rs = alpha / sqrtf(wave_sum_fast(s) * (1.f / DM) + EPS);
;         float s2 = 0.f;
; #pragma unroll
;         for (int j = 0; j < 4; ++j) { b[j] = b[j] + f[j] * rs * gp[j]; s2 += (b[j].x * b[j].x + b[j].y * b[j].y) + (b[j].z * b[j].z + b[j].w * b[j].w);
;             ((f32x4*)(H + (size_t)m * DM))[lane + 64 * j] = b[j]; }
;         if (gnext) {
;             const float r2 = 1.f / sqrtf(wave_sum_fast(s2) * (1.f / DM) + EPS);
;             u32x2* o8 = (u32x2*)(XN + (size_t)m * DM) + lane;
; #pragma unroll
;             for (int j = 0; j < 4; ++j) { u32x2 w; w.x = pk2(b[j].x * r2 * gn[j].x, b[j].y * r2 * gn[j].y); w.y = pk2(b[j].z * r2 * gn[j].z, b[j].w * r2 * gn[j].w); o8[64 * j] = w; }
;         }
;         if (more) {
; #pragma unroll
;             for (int j = 0; j < 4; ++j) { f[j] = f2[j]; b[j] = b2[j]; } }
	v_mul_f32_e32 v0, v16, v96
	v_mul_f32_e32 v1, v17, v96
	v_mul_f32_e32 v2, v18, v96
	v_mul_f32_e32 v3, v19, v96
	v_mul_f32_e32 v4, v20, v96
	v_mul_f32_e32 v5, v21, v96
	v_mul_f32_e32 v6, v22, v96
	v_mul_f32_e32 v7, v23, v96
	v_mul_f32_e32 v8, v24, v96
	v_mul_f32_e32 v9, v25, v96
	v_mul_f32_e32 v10, v26, v96
	v_mul_f32_e32 v11, v27, v96
	v_mul_f32_e32 v12, v28, v96
	v_mul_f32_e32 v13, v29, v96
	v_mul_f32_e32 v14, v30, v96
	v_mul_f32_e32 v15, v31, v96
	v_mul_f32_e32 v0, v128, v0
	v_mul_f32_e32 v1, v129, v1
	v_mul_f32_e32 v2, v130, v2
	v_mul_f32_e32 v3, v131, v3
	v_mul_f32_e32 v4, v132, v4
	v_mul_f32_e32 v5, v133, v5
	v_mul_f32_e32 v6, v134, v6
	v_mul_f32_e32 v7, v135, v7
	v_mul_f32_e32 v8, v136, v8
	v_mul_f32_e32 v9, v137, v9
	v_mul_f32_e32 v10, v138, v10
	v_mul_f32_e32 v11, v139, v11
	v_mul_f32_e32 v12, v140, v12
	v_mul_f32_e32 v13, v141, v13
	v_mul_f32_e32 v14, v142, v14
	v_mul_f32_e32 v15, v143, v15
	v_cvt_pk_bf16_f32 v148, v0, v1
	v_cvt_pk_bf16_f32 v149, v2, v3
	global_store_dwordx2 v145, v[148:149], s[42:43] offset:0
	v_cvt_pk_bf16_f32 v150, v4, v5
	v_cvt_pk_bf16_f32 v151, v6, v7
	global_store_dwordx2 v145, v[150:151], s[42:43] offset:512
	v_cvt_pk_bf16_f32 v152, v8, v9
	v_cvt_pk_bf16_f32 v153, v10, v11
	global_store_dwordx2 v145, v[152:153], s[42:43] offset:1024
	v_cvt_pk_bf16_f32 v154, v12, v13
	v_cvt_pk_bf16_f32 v155, v14, v15
	global_store_dwordx2 v145, v[154:155], s[42:43] offset:1536
	s_add_u32 s40, s40, 0x8000
	s_addc_u32 s41, s41, 0
	s_add_u32 s42, s42, 0x4000
	s_addc_u32 s43, s43, 0
	global_load_dwordx4 v[0:3], v144, s[24:25] offset:0
	global_load_dwordx4 v[4:7], v144, s[24:25] offset:1024
	global_load_dwordx4 v[8:11], v144, s[24:25] offset:2048
	global_load_dwordx4 v[12:15], v144, s[24:25] offset:3072
	global_load_dwordx4 v[16:19], v144, s[26:27] offset:0
	global_load_dwordx4 v[20:23], v144, s[26:27] offset:1024
	global_load_dwordx4 v[24:27], v144, s[26:27] offset:2048
	global_load_dwordx4 v[28:31], v144, s[26:27] offset:3072
	s_add_u32 s24, s24, 0x8000
	s_addc_u32 s25, s25, 0
	s_add_u32 s26, s26, 0x8000
	s_addc_u32 s27, s27, 0
	s_waitcnt vmcnt(32)
	v_mul_f32_e32 v96, v33, v33
	v_mul_f32_e32 v98, v35, v35
	v_fmac_f32_e32 v96, v32, v32
	v_fmac_f32_e32 v98, v34, v34
	v_add_f32_e32 v96, v96, v98
	v_mul_f32_e32 v97, v37, v37
	v_mul_f32_e32 v98, v39, v39
	v_fmac_f32_e32 v97, v36, v36
	v_fmac_f32_e32 v98, v38, v38
	v_add_f32_e32 v97, v97, v98
	v_add_f32_e32 v96, v97, v96
	v_mul_f32_e32 v97, v41, v41
	v_mul_f32_e32 v98, v43, v43
	v_fmac_f32_e32 v97, v40, v40
	v_fmac_f32_e32 v98, v42, v42
	v_add_f32_e32 v97, v97, v98
	v_add_f32_e32 v96, v97, v96
	v_mul_f32_e32 v97, v45, v45
	v_mul_f32_e32 v98, v47, v47
	v_fmac_f32_e32 v97, v44, v44
	v_fmac_f32_e32 v98, v46, v46
	v_add_f32_e32 v97, v97, v98
	v_add_f32_e32 v96, v97, v96
	s_nop 1
	v_add_f32_dpp v96, v96, v96 quad_perm:[1,0,3,2] row_mask:0xf bank_mask:0xf bound_ctrl:1
	s_nop 1
	v_add_f32_dpp v96, v96, v96 quad_perm:[2,3,0,1] row_mask:0xf bank_mask:0xf bound_ctrl:1
	s_nop 1
	v_add_f32_dpp v96, v96, v96 row_half_mirror row_mask:0xf bank_mask:0xf bound_ctrl:1
	s_nop 1
	v_add_f32_dpp v96, v96, v96 row_mirror row_mask:0xf bank_mask:0xf bound_ctrl:1
	v_mov_b32_e32 v97, v96
	s_nop 1
	v_permlane16_swap_b32_e32 v96, v97
	v_add_f32_e32 v96, v96, v97
	v_mov_b32_e32 v97, v96
	s_nop 1
	v_permlane32_swap_b32_e32 v96, v97
	v_add_f32_e32 v96, v96, v97
	v_fmamk_f32 v96, v96, 0x3a800000, v146
	v_mul_f32_e32 v97, 0x4f800000, v96
	v_cmp_gt_f32_e32 vcc, s33, v96
	s_nop 1
	v_cndmask_b32_e32 v96, v96, v97, vcc
	v_sqrt_f32_e32 v97, v96
	s_nop 0
	v_add_u32_e32 v98, -1, v97
	v_fma_f32 v99, -v98, v97, v96
	v_cmp_ge_f32_e64 s[4:5], 0, v99
	v_add_u32_e32 v99, 1, v97
	s_nop 0
	v_cndmask_b32_e64 v98, v97, v98, s[4:5]
	v_fma_f32 v97, -v99, v97, v96
	v_cmp_lt_f32_e64 s[4:5], 0, v97
	s_nop 1
	v_cndmask_b32_e64 v97, v98, v99, s[4:5]
	v_mul_f32_e32 v98, 0x37800000, v97
	v_cndmask_b32_e32 v97, v97, v98, vcc
	v_cmp_class_f32_e32 vcc, v96, v147
	s_nop 1
	v_cndmask_b32_e32 v96, v97, v96, vcc
	v_div_scale_f32 v97, s[4:5], v96, v96, 0.5
	v_rcp_f32_e32 v98, v97
	s_nop 0
	v_fma_f32 v99, -v97, v98, 1.0
	v_fmac_f32_e32 v98, v99, v98
	v_div_scale_f32 v99, vcc, 0.5, v96, 0.5
	v_mul_f32_e32 v100, v99, v98
	v_fma_f32 v101, -v97, v100, v99
	v_fmac_f32_e32 v100, v101, v98
	v_fma_f32 v97, -v97, v100, v99
	v_div_fmas_f32 v97, v97, v98, v100
	v_div_fixup_f32 v96, v97, v96, 0.5
	v_mul_f32_e32 v32, v32, v96
	v_mul_f32_e32 v33, v33, v96
	v_mul_f32_e32 v34, v34, v96
	v_mul_f32_e32 v35, v35, v96
	v_mul_f32_e32 v36, v36, v96
	v_mul_f32_e32 v37, v37, v96
	v_mul_f32_e32 v38, v38, v96
	v_mul_f32_e32 v39, v39, v96
	v_mul_f32_e32 v40, v40, v96
	v_mul_f32_e32 v41, v41, v96
	v_mul_f32_e32 v42, v42, v96
	v_mul_f32_e32 v43, v43, v96
	v_mul_f32_e32 v44, v44, v96
	v_mul_f32_e32 v45, v45, v96
	v_mul_f32_e32 v46, v46, v96
	v_mul_f32_e32 v47, v47, v96
	v_fmac_f32_e32 v48, v112, v32
	v_fmac_f32_e32 v49, v113, v33
	v_fmac_f32_e32 v50, v114, v34
	v_fmac_f32_e32 v51, v115, v35
	v_fmac_f32_e32 v52, v116, v36
	v_fmac_f32_e32 v53, v117, v37
	v_fmac_f32_e32 v54, v118, v38
	v_fmac_f32_e32 v55, v119, v39
	v_fmac_f32_e32 v56, v120, v40
	v_fmac_f32_e32 v57, v121, v41
	v_fmac_f32_e32 v58, v122, v42
	v_fmac_f32_e32 v59, v123, v43
	v_fmac_f32_e32 v60, v124, v44
	v_fmac_f32_e32 v61, v125, v45
	v_fmac_f32_e32 v62, v126, v46
	v_fmac_f32_e32 v63, v127, v47
	global_store_dwordx4 v144, v[48:51], s[40:41] offset:0
	global_store_dwordx4 v144, v[52:55], s[40:41] offset:1024
	global_store_dwordx4 v144, v[56:59], s[40:41] offset:2048
	global_store_dwordx4 v144, v[60:63], s[40:41] offset:3072
	v_mul_f32_e32 v96, v49, v49
	v_mul_f32_e32 v98, v51, v51
	v_fmac_f32_e32 v96, v48, v48
; __device__ __forceinline__ unsigned pk2(float lo, float hi) { f32x2 v = {lo, hi}; bf16x2_t b = __builtin_convertvector(v, bf16x2_t); return __builtin_bit_cast(unsigned, b); }
; __device__ __forceinline__ void phase_rowpass(const Ctx& p, const float* F, int base_is_x, float alpha, const float* gpost, const float* gnext, bf16_t* XN, const float* PART, int nsplit) {
;     ...
;     for (int m = gw; m < MR; m += NGW) {
;         const bool more = m + NGW < MR;
;         if (more) loadrow(m + NGW, f2, b2);
;         float s = 0.f;
; #pragma unroll
;         for (int j = 0; j < 4; ++j) s += (f[j].x * f[j].x + f[j].y * f[j].y) + (f[j].z * f[j].z + f[j].w * f[j].w);
;         const float rs = alpha / sqrtf(wave_sum_fast(s) * (1.f / DM) + EPS);
;         float s2 = 0.f;
; #pragma unroll
;         for (int j = 0; j < 4; ++j) { b[j] = b[j] + f[j] * rs * gp[j]; s2 += (b[j].x * b[j].x + b[j].y * b[j].y) + (b[j].z * b[j].z + b[j].w * b[j].w);
;             ((f32x4*)(H + (size_t)m * DM))[lane + 64 * j] = b[j]; }
;         if (gnext) {
;             const float r2 = 1.f / sqrtf(wave_sum_fast(s2) * (1.f / DM) + EPS);
;             u32x2* o8 = (u32x2*)(XN + (size_t)m * DM) + lane;
; #pragma unroll
;             for (int j = 0; j < 4; ++j) { u32x2 w; w.x = pk2(b[j].x * r2 * gn[j].x, b[j].y * r2 * gn[j].y); w.y = pk2(b[j].z * r2 * gn[j].z, b[j].w * r2 * gn[j].w); o8[64 * j] = w; }
;         }
;         if (more) {
; #pragma unroll
;             for (int j = 0; j < 4; ++j) { f[j] = f2[j]; b[j] = b2[j]; } }
	v_fmac_f32_e32 v98, v50, v50
	v_add_f32_e32 v96, v96, v98
	v_mul_f32_e32 v97, v53, v53
	v_mul_f32_e32 v98, v55, v55
	v_fmac_f32_e32 v97, v52, v52
	v_fmac_f32_e32 v98, v54, v54
	v_add_f32_e32 v97, v97, v98
	v_add_f32_e32 v96, v97, v96
	v_mul_f32_e32 v97, v57, v57
	v_mul_f32_e32 v98, v59, v59
	v_fmac_f32_e32 v97, v56, v56
	v_fmac_f32_e32 v98, v58, v58
	v_add_f32_e32 v97, v97, v98
	v_add_f32_e32 v96, v97, v96
	v_mul_f32_e32 v97, v61, v61
	v_mul_f32_e32 v98, v63, v63
	v_fmac_f32_e32 v97, v60, v60
	v_fmac_f32_e32 v98, v62, v62
	v_add_f32_e32 v97, v97, v98
	v_add_f32_e32 v96, v97, v96
	s_nop 1
	v_add_f32_dpp v96, v96, v96 quad_perm:[1,0,3,2] row_mask:0xf bank_mask:0xf bound_ctrl:1
	s_nop 1
	v_add_f32_dpp v96, v96, v96 quad_perm:[2,3,0,1] row_mask:0xf bank_mask:0xf bound_ctrl:1
	s_nop 1
	v_add_f32_dpp v96, v96, v96 row_half_mirror row_mask:0xf bank_mask:0xf bound_ctrl:1
	s_nop 1
	v_add_f32_dpp v96, v96, v96 row_mirror row_mask:0xf bank_mask:0xf bound_ctrl:1
	v_mov_b32_e32 v97, v96
	s_nop 1
	v_permlane16_swap_b32_e32 v96, v97
	v_add_f32_e32 v96, v96, v97
	v_mov_b32_e32 v97, v96
	s_nop 1
	v_permlane32_swap_b32_e32 v96, v97
	v_add_f32_e32 v96, v96, v97
	v_fmamk_f32 v96, v96, 0x3a800000, v146
	v_mul_f32_e32 v97, 0x4f800000, v96
	v_cmp_gt_f32_e32 vcc, s33, v96
	s_nop 1
	v_cndmask_b32_e32 v96, v96, v97, vcc
	v_sqrt_f32_e32 v97, v96
	s_nop 0
	v_add_u32_e32 v98, -1, v97
	v_fma_f32 v99, -v98, v97, v96
	v_cmp_ge_f32_e64 s[4:5], 0, v99
	v_add_u32_e32 v99, 1, v97
	s_nop 0
	v_cndmask_b32_e64 v98, v97, v98, s[4:5]
	v_fma_f32 v97, -v99, v97, v96
	v_cmp_lt_f32_e64 s[4:5], 0, v97
	s_nop 1
	v_cndmask_b32_e64 v97, v98, v99, s[4:5]
	v_mul_f32_e32 v98, 0x37800000, v97
	v_cndmask_b32_e32 v97, v97, v98, vcc
	v_cmp_class_f32_e32 vcc, v96, v147
	s_nop 1
	v_cndmask_b32_e32 v96, v97, v96, vcc
	v_div_scale_f32 v97, s[4:5], v96, v96, 1.0
	v_rcp_f32_e32 v98, v97
	s_nop 0
	v_fma_f32 v99, -v97, v98, 1.0
	v_fmac_f32_e32 v98, v99, v98
	v_div_scale_f32 v99, vcc, 1.0, v96, 1.0
	v_mul_f32_e32 v100, v99, v98
	v_fma_f32 v101, -v97, v100, v99
	v_fmac_f32_e32 v100, v101, v98
	v_fma_f32 v97, -v97, v100, v99
	v_div_fmas_f32 v97, v97, v98, v100
	v_div_fixup_f32 v96, v97, v96, 1.0
	v_mul_f32_e32 v32, v48, v96
	v_mul_f32_e32 v33, v49, v96
	v_mul_f32_e32 v34, v50, v96
	v_mul_f32_e32 v35, v51, v96
	v_mul_f32_e32 v36, v52, v96
	v_mul_f32_e32 v37, v53, v96
	v_mul_f32_e32 v38, v54, v96
	v_mul_f32_e32 v39, v55, v96
	v_mul_f32_e32 v40, v56, v96
	v_mul_f32_e32 v41, v57, v96
	v_mul_f32_e32 v42, v58, v96
	v_mul_f32_e32 v43, v59, v96
	v_mul_f32_e32 v44, v60, v96
	v_mul_f32_e32 v45, v61, v96
	v_mul_f32_e32 v46, v62, v96
	v_mul_f32_e32 v47, v63, v96
	v_mul_f32_e32 v32, v128, v32
	v_mul_f32_e32 v33, v129, v33
	v_mul_f32_e32 v34, v130, v34
	v_mul_f32_e32 v35, v131, v35
	v_mul_f32_e32 v36, v132, v36
	v_mul_f32_e32 v37, v133, v37
	v_mul_f32_e32 v38, v134, v38
	v_mul_f32_e32 v39, v135, v39
	v_mul_f32_e32 v40, v136, v40
	v_mul_f32_e32 v41, v137, v41
	v_mul_f32_e32 v42, v138, v42
	v_mul_f32_e32 v43, v139, v43
	v_mul_f32_e32 v44, v140, v44
	v_mul_f32_e32 v45, v141, v45
	v_mul_f32_e32 v46, v142, v46
	v_mul_f32_e32 v47, v143, v47
	v_cvt_pk_bf16_f32 v148, v32, v33
	v_cvt_pk_bf16_f32 v149, v34, v35
	global_store_dwordx2 v145, v[148:149], s[42:43] offset:0
	v_cvt_pk_bf16_f32 v150, v36, v37
	v_cvt_pk_bf16_f32 v151, v38, v39
	global_store_dwordx2 v145, v[150:151], s[42:43] offset:512
	v_cvt_pk_bf16_f32 v152, v40, v41
	v_cvt_pk_bf16_f32 v153, v42, v43
	global_store_dwordx2 v145, v[152:153], s[42:43] offset:1024
	v_cvt_pk_bf16_f32 v154, v44, v45
	v_cvt_pk_bf16_f32 v155, v46, v47
	global_store_dwordx2 v145, v[154:155], s[42:43] offset:1536
	s_add_u32 s40, s40, 0x8000
	s_addc_u32 s41, s41, 0
	s_add_u32 s42, s42, 0x4000
	s_addc_u32 s43, s43, 0
	global_load_dwordx4 v[32:35], v144, s[24:25] offset:0
	global_load_dwordx4 v[36:39], v144, s[24:25] offset:1024
	global_load_dwordx4 v[40:43], v144, s[24:25] offset:2048
	global_load_dwordx4 v[44:47], v144, s[24:25] offset:3072
	global_load_dwordx4 v[48:51], v144, s[26:27] offset:0
	global_load_dwordx4 v[52:55], v144, s[26:27] offset:1024
	global_load_dwordx4 v[56:59], v144, s[26:27] offset:2048
	global_load_dwordx4 v[60:63], v144, s[26:27] offset:3072
	s_add_u32 s24, s24, 0x8000
	s_addc_u32 s25, s25, 0
	s_add_u32 s26, s26, 0x8000
	s_addc_u32 s27, s27, 0
	s_waitcnt vmcnt(32)
; __device__ __forceinline__ unsigned pk2(float lo, float hi) { f32x2 v = {lo, hi}; bf16x2_t b = __builtin_convertvector(v, bf16x2_t); return __builtin_bit_cast(unsigned, b); }
; __device__ __forceinline__ void phase_rowpass(const Ctx& p, const float* F, int base_is_x, float alpha, const float* gpost, const float* gnext, bf16_t* XN, const float* PART, int nsplit) {
;     ...
;     for (int m = gw; m < MR; m += NGW) {
;         const bool more = m + NGW < MR;
;         if (more) loadrow(m + NGW, f2, b2);
;         float s = 0.f;
; #pragma unroll
;         for (int j = 0; j < 4; ++j) s += (f[j].x * f[j].x + f[j].y * f[j].y) + (f[j].z * f[j].z + f[j].w * f[j].w);
;         const float rs = alpha / sqrtf(wave_sum_fast(s) * (1.f / DM) + EPS);
;         float s2 = 0.f;
; #pragma unroll
;         for (int j = 0; j < 4; ++j) { b[j] = b[j] + f[j] * rs * gp[j]; s2 += (b[j].x * b[j].x + b[j].y * b[j].y) + (b[j].z * b[j].z + b[j].w * b[j].w);
;             ((f32x4*)(H + (size_t)m * DM))[lane + 64 * j] = b[j]; }
;         if (gnext) {
;             const float r2 = 1.f / sqrtf(wave_sum_fast(s2) * (1.f / DM) + EPS);
;             u32x2* o8 = (u32x2*)(XN + (size_t)m * DM) + lane;
; #pragma unroll
;             for (int j = 0; j < 4; ++j) { u32x2 w; w.x = pk2(b[j].x * r2 * gn[j].x, b[j].y * r2 * gn[j].y); w.y = pk2(b[j].z * r2 * gn[j].z, b[j].w * r2 * gn[j].w); o8[64 * j] = w; }
;         }
;         if (more) {
; #pragma unroll
;             for (int j = 0; j < 4; ++j) { f[j] = f2[j]; b[j] = b2[j]; } }
	v_mul_f32_e32 v96, v65, v65
	v_mul_f32_e32 v98, v67, v67
	v_fmac_f32_e32 v96, v64, v64
	v_fmac_f32_e32 v98, v66, v66
	v_add_f32_e32 v96, v96, v98
	v_mul_f32_e32 v97, v69, v69
	v_mul_f32_e32 v98, v71, v71
	v_fmac_f32_e32 v97, v68, v68
	v_fmac_f32_e32 v98, v70, v70
	v_add_f32_e32 v97, v97, v98
	v_add_f32_e32 v96, v97, v96
	v_mul_f32_e32 v97, v73, v73
	v_mul_f32_e32 v98, v75, v75
	v_fmac_f32_e32 v97, v72, v72
	v_fmac_f32_e32 v98, v74, v74
	v_add_f32_e32 v97, v97, v98
	v_add_f32_e32 v96, v97, v96
	v_mul_f32_e32 v97, v77, v77
	v_mul_f32_e32 v98, v79, v79
	v_fmac_f32_e32 v97, v76, v76
	v_fmac_f32_e32 v98, v78, v78
	v_add_f32_e32 v97, v97, v98
	v_add_f32_e32 v96, v97, v96
	s_nop 1
	v_add_f32_dpp v96, v96, v96 quad_perm:[1,0,3,2] row_mask:0xf bank_mask:0xf bound_ctrl:1
	s_nop 1
	v_add_f32_dpp v96, v96, v96 quad_perm:[2,3,0,1] row_mask:0xf bank_mask:0xf bound_ctrl:1
	s_nop 1
	v_add_f32_dpp v96, v96, v96 row_half_mirror row_mask:0xf bank_mask:0xf bound_ctrl:1
	s_nop 1
	v_add_f32_dpp v96, v96, v96 row_mirror row_mask:0xf bank_mask:0xf bound_ctrl:1
	v_mov_b32_e32 v97, v96
	s_nop 1
	v_permlane16_swap_b32_e32 v96, v97
	v_add_f32_e32 v96, v96, v97
	v_mov_b32_e32 v97, v96
	s_nop 1
	v_permlane32_swap_b32_e32 v96, v97
	v_add_f32_e32 v96, v96, v97
	v_fmamk_f32 v96, v96, 0x3a800000, v146
	v_mul_f32_e32 v97, 0x4f800000, v96
	v_cmp_gt_f32_e32 vcc, s33, v96
	s_nop 1
	v_cndmask_b32_e32 v96, v96, v97, vcc
	v_sqrt_f32_e32 v97, v96
	s_nop 0
	v_add_u32_e32 v98, -1, v97
	v_fma_f32 v99, -v98, v97, v96
	v_cmp_ge_f32_e64 s[4:5], 0, v99
	v_add_u32_e32 v99, 1, v97
	s_nop 0
	v_cndmask_b32_e64 v98, v97, v98, s[4:5]
	v_fma_f32 v97, -v99, v97, v96
	v_cmp_lt_f32_e64 s[4:5], 0, v97
	s_nop 1
	v_cndmask_b32_e64 v97, v98, v99, s[4:5]
	v_mul_f32_e32 v98, 0x37800000, v97
	v_cndmask_b32_e32 v97, v97, v98, vcc
	v_cmp_class_f32_e32 vcc, v96, v147
	s_nop 1
	v_cndmask_b32_e32 v96, v97, v96, vcc
	v_div_scale_f32 v97, s[4:5], v96, v96, 0.5
	v_rcp_f32_e32 v98, v97
	s_nop 0
	v_fma_f32 v99, -v97, v98, 1.0
	v_fmac_f32_e32 v98, v99, v98
	v_div_scale_f32 v99, vcc, 0.5, v96, 0.5
	v_mul_f32_e32 v100, v99, v98
	v_fma_f32 v101, -v97, v100, v99
	v_fmac_f32_e32 v100, v101, v98
	v_fma_f32 v97, -v97, v100, v99
	v_div_fmas_f32 v97, v97, v98, v100
	v_div_fixup_f32 v96, v97, v96, 0.5
	v_mul_f32_e32 v64, v64, v96
	v_mul_f32_e32 v65, v65, v96
	v_mul_f32_e32 v66, v66, v96
	v_mul_f32_e32 v67, v67, v96
	v_mul_f32_e32 v68, v68, v96
	v_mul_f32_e32 v69, v69, v96
	v_mul_f32_e32 v70, v70, v96
	v_mul_f32_e32 v71, v71, v96
	v_mul_f32_e32 v72, v72, v96
	v_mul_f32_e32 v73, v73, v96
	v_mul_f32_e32 v74, v74, v96
	v_mul_f32_e32 v75, v75, v96
	v_mul_f32_e32 v76, v76, v96
	v_mul_f32_e32 v77, v77, v96
	v_mul_f32_e32 v78, v78, v96
	v_mul_f32_e32 v79, v79, v96
	v_fmac_f32_e32 v80, v112, v64
	v_fmac_f32_e32 v81, v113, v65
	v_fmac_f32_e32 v82, v114, v66
	v_fmac_f32_e32 v83, v115, v67
	v_fmac_f32_e32 v84, v116, v68
	v_fmac_f32_e32 v85, v117, v69
	v_fmac_f32_e32 v86, v118, v70
	v_fmac_f32_e32 v87, v119, v71
	v_fmac_f32_e32 v88, v120, v72
	v_fmac_f32_e32 v89, v121, v73
	v_fmac_f32_e32 v90, v122, v74
	v_fmac_f32_e32 v91, v123, v75
	v_fmac_f32_e32 v92, v124, v76
	v_fmac_f32_e32 v93, v125, v77
	v_fmac_f32_e32 v94, v126, v78
	v_fmac_f32_e32 v95, v127, v79
	global_store_dwordx4 v144, v[80:83], s[40:41] offset:0
	global_store_dwordx4 v144, v[84:87], s[40:41] offset:1024
	global_store_dwordx4 v144, v[88:91], s[40:41] offset:2048
	global_store_dwordx4 v144, v[92:95], s[40:41] offset:3072
	v_mul_f32_e32 v96, v81, v81
	v_mul_f32_e32 v98, v83, v83
	v_fmac_f32_e32 v96, v80, v80
	v_fmac_f32_e32 v98, v82, v82
	v_add_f32_e32 v96, v96, v98
	v_mul_f32_e32 v97, v85, v85
	v_mul_f32_e32 v98, v87, v87
	v_fmac_f32_e32 v97, v84, v84
	v_fmac_f32_e32 v98, v86, v86
	v_add_f32_e32 v97, v97, v98
	v_add_f32_e32 v96, v97, v96
	v_mul_f32_e32 v97, v89, v89
	v_mul_f32_e32 v98, v91, v91
	v_fmac_f32_e32 v97, v88, v88
	v_fmac_f32_e32 v98, v90, v90
	v_add_f32_e32 v97, v97, v98
	v_add_f32_e32 v96, v97, v96
	v_mul_f32_e32 v97, v93, v93
	v_mul_f32_e32 v98, v95, v95
	v_fmac_f32_e32 v97, v92, v92
	v_fmac_f32_e32 v98, v94, v94
	v_add_f32_e32 v97, v97, v98
	v_add_f32_e32 v96, v97, v96
	s_nop 1
	v_add_f32_dpp v96, v96, v96 quad_perm:[1,0,3,2] row_mask:0xf bank_mask:0xf bound_ctrl:1
	s_nop 1
	v_add_f32_dpp v96, v96, v96 quad_perm:[2,3,0,1] row_mask:0xf bank_mask:0xf bound_ctrl:1
	s_nop 1
	v_add_f32_dpp v96, v96, v96 row_half_mirror row_mask:0xf bank_mask:0xf bound_ctrl:1
	s_nop 1
	v_add_f32_dpp v96, v96, v96 row_mirror row_mask:0xf bank_mask:0xf bound_ctrl:1
	v_mov_b32_e32 v97, v96
	s_nop 1
	v_permlane16_swap_b32_e32 v96, v97
	v_add_f32_e32 v96, v96, v97
	v_mov_b32_e32 v97, v96
	s_nop 1
	v_permlane32_swap_b32_e32 v96, v97
	v_add_f32_e32 v96, v96, v97
	v_fmamk_f32 v96, v96, 0x3a800000, v146
	v_mul_f32_e32 v97, 0x4f800000, v96
	v_cmp_gt_f32_e32 vcc, s33, v96
	s_nop 1
	v_cndmask_b32_e32 v96, v96, v97, vcc
	v_sqrt_f32_e32 v97, v96
	s_nop 0
	v_add_u32_e32 v98, -1, v97
	v_fma_f32 v99, -v98, v97, v96
	v_cmp_ge_f32_e64 s[4:5], 0, v99
	v_add_u32_e32 v99, 1, v97
	s_nop 0
	v_cndmask_b32_e64 v98, v97, v98, s[4:5]
	v_fma_f32 v97, -v99, v97, v96
	v_cmp_lt_f32_e64 s[4:5], 0, v97
	s_nop 1
	v_cndmask_b32_e64 v97, v98, v99, s[4:5]
	v_mul_f32_e32 v98, 0x37800000, v97
	v_cndmask_b32_e32 v97, v97, v98, vcc
	v_cmp_class_f32_e32 vcc, v96, v147
	s_nop 1
	v_cndmask_b32_e32 v96, v97, v96, vcc
	v_div_scale_f32 v97, s[4:5], v96, v96, 1.0
	v_rcp_f32_e32 v98, v97
	s_nop 0
	v_fma_f32 v99, -v97, v98, 1.0
	v_fmac_f32_e32 v98, v99, v98
	v_div_scale_f32 v99, vcc, 1.0, v96, 1.0
	v_mul_f32_e32 v100, v99, v98
	v_fma_f32 v101, -v97, v100, v99
	v_fmac_f32_e32 v100, v101, v98
	v_fma_f32 v97, -v97, v100, v99
; __device__ __forceinline__ unsigned pk2(float lo, float hi) { f32x2 v = {lo, hi}; bf16x2_t b = __builtin_convertvector(v, bf16x2_t); return __builtin_bit_cast(unsigned, b); }
; __device__ __forceinline__ void phase_rowpass(const Ctx& p, const float* F, int base_is_x, float alpha, const float* gpost, const float* gnext, bf16_t* XN, const float* PART, int nsplit) {
;     ...
;     for (int m = gw; m < MR; m += NGW) {
;         const bool more = m + NGW < MR;
;         if (more) loadrow(m + NGW, f2, b2);
;         float s = 0.f;
; #pragma unroll
;         for (int j = 0; j < 4; ++j) s += (f[j].x * f[j].x + f[j].y * f[j].y) + (f[j].z * f[j].z + f[j].w * f[j].w);
;         const float rs = alpha / sqrtf(wave_sum_fast(s) * (1.f / DM) + EPS);
;         float s2 = 0.f;
; #pragma unroll
;         for (int j = 0; j < 4; ++j) { b[j] = b[j] + f[j] * rs * gp[j]; s2 += (b[j].x * b[j].x + b[j].y * b[j].y) + (b[j].z * b[j].z + b[j].w * b[j].w);
;             ((f32x4*)(H + (size_t)m * DM))[lane + 64 * j] = b[j]; }
;         if (gnext) {
;             const float r2 = 1.f / sqrtf(wave_sum_fast(s2) * (1.f / DM) + EPS);
;             u32x2* o8 = (u32x2*)(XN + (size_t)m * DM) + lane;
; #pragma unroll
;             for (int j = 0; j < 4; ++j) { u32x2 w; w.x = pk2(b[j].x * r2 * gn[j].x, b[j].y * r2 * gn[j].y); w.y = pk2(b[j].z * r2 * gn[j].z, b[j].w * r2 * gn[j].w); o8[64 * j] = w; }
;         }
;         if (more) {
; #pragma unroll
;             for (int j = 0; j < 4; ++j) { f[j] = f2[j]; b[j] = b2[j]; } }
	v_div_fmas_f32 v97, v97, v98, v100
	v_div_fixup_f32 v96, v97, v96, 1.0
	v_mul_f32_e32 v64, v80, v96
	v_mul_f32_e32 v65, v81, v96
	v_mul_f32_e32 v66, v82, v96
	v_mul_f32_e32 v67, v83, v96
	v_mul_f32_e32 v68, v84, v96
	v_mul_f32_e32 v69, v85, v96
	v_mul_f32_e32 v70, v86, v96
	v_mul_f32_e32 v71, v87, v96
	v_mul_f32_e32 v72, v88, v96
	v_mul_f32_e32 v73, v89, v96
	v_mul_f32_e32 v74, v90, v96
	v_mul_f32_e32 v75, v91, v96
	v_mul_f32_e32 v76, v92, v96
	v_mul_f32_e32 v77, v93, v96
	v_mul_f32_e32 v78, v94, v96
	v_mul_f32_e32 v79, v95, v96
	v_mul_f32_e32 v64, v128, v64
	v_mul_f32_e32 v65, v129, v65
	v_mul_f32_e32 v66, v130, v66
	v_mul_f32_e32 v67, v131, v67
	v_mul_f32_e32 v68, v132, v68
	v_mul_f32_e32 v69, v133, v69
	v_mul_f32_e32 v70, v134, v70
	v_mul_f32_e32 v71, v135, v71
	v_mul_f32_e32 v72, v136, v72
	v_mul_f32_e32 v73, v137, v73
	v_mul_f32_e32 v74, v138, v74
	v_mul_f32_e32 v75, v139, v75
	v_mul_f32_e32 v76, v140, v76
	v_mul_f32_e32 v77, v141, v77
	v_mul_f32_e32 v78, v142, v78
	v_mul_f32_e32 v79, v143, v79
	v_cvt_pk_bf16_f32 v148, v64, v65
	v_cvt_pk_bf16_f32 v149, v66, v67
	global_store_dwordx2 v145, v[148:149], s[42:43] offset:0
	v_cvt_pk_bf16_f32 v150, v68, v69
	v_cvt_pk_bf16_f32 v151, v70, v71
	global_store_dwordx2 v145, v[150:151], s[42:43] offset:512
	v_cvt_pk_bf16_f32 v152, v72, v73
	v_cvt_pk_bf16_f32 v153, v74, v75
	global_store_dwordx2 v145, v[152:153], s[42:43] offset:1024
	v_cvt_pk_bf16_f32 v154, v76, v77
	v_cvt_pk_bf16_f32 v155, v78, v79
	global_store_dwordx2 v145, v[154:155], s[42:43] offset:1536
	s_add_u32 s40, s40, 0x8000
	s_addc_u32 s41, s41, 0
	s_add_u32 s42, s42, 0x4000
	s_addc_u32 s43, s43, 0
	s_waitcnt vmcnt(24)
	v_mul_f32_e32 v96, v1, v1
	v_mul_f32_e32 v98, v3, v3
	v_fmac_f32_e32 v96, v0, v0
	v_fmac_f32_e32 v98, v2, v2
	v_add_f32_e32 v96, v96, v98
	v_mul_f32_e32 v97, v5, v5
	v_mul_f32_e32 v98, v7, v7
	v_fmac_f32_e32 v97, v4, v4
	v_fmac_f32_e32 v98, v6, v6
	v_add_f32_e32 v97, v97, v98
	v_add_f32_e32 v96, v97, v96
	v_mul_f32_e32 v97, v9, v9
	v_mul_f32_e32 v98, v11, v11
	v_fmac_f32_e32 v97, v8, v8
	v_fmac_f32_e32 v98, v10, v10
	v_add_f32_e32 v97, v97, v98
	v_add_f32_e32 v96, v97, v96
	v_mul_f32_e32 v97, v13, v13
	v_mul_f32_e32 v98, v15, v15
	v_fmac_f32_e32 v97, v12, v12
	v_fmac_f32_e32 v98, v14, v14
	v_add_f32_e32 v97, v97, v98
	v_add_f32_e32 v96, v97, v96
	s_nop 1
	v_add_f32_dpp v96, v96, v96 quad_perm:[1,0,3,2] row_mask:0xf bank_mask:0xf bound_ctrl:1
	s_nop 1
	v_add_f32_dpp v96, v96, v96 quad_perm:[2,3,0,1] row_mask:0xf bank_mask:0xf bound_ctrl:1
	s_nop 1
	v_add_f32_dpp v96, v96, v96 row_half_mirror row_mask:0xf bank_mask:0xf bound_ctrl:1
	s_nop 1
	v_add_f32_dpp v96, v96, v96 row_mirror row_mask:0xf bank_mask:0xf bound_ctrl:1
	v_mov_b32_e32 v97, v96
	s_nop 1
	v_permlane16_swap_b32_e32 v96, v97
	v_add_f32_e32 v96, v96, v97
	v_mov_b32_e32 v97, v96
	s_nop 1
	v_permlane32_swap_b32_e32 v96, v97
	v_add_f32_e32 v96, v96, v97
	v_fmamk_f32 v96, v96, 0x3a800000, v146
	v_mul_f32_e32 v97, 0x4f800000, v96
	v_cmp_gt_f32_e32 vcc, s33, v96
	s_nop 1
	v_cndmask_b32_e32 v96, v96, v97, vcc
	v_sqrt_f32_e32 v97, v96
	s_nop 0
	v_add_u32_e32 v98, -1, v97
	v_fma_f32 v99, -v98, v97, v96
	v_cmp_ge_f32_e64 s[4:5], 0, v99
	v_add_u32_e32 v99, 1, v97
	s_nop 0
	v_cndmask_b32_e64 v98, v97, v98, s[4:5]
	v_fma_f32 v97, -v99, v97, v96
	v_cmp_lt_f32_e64 s[4:5], 0, v97
	s_nop 1
	v_cndmask_b32_e64 v97, v98, v99, s[4:5]
	v_mul_f32_e32 v98, 0x37800000, v97
	v_cndmask_b32_e32 v97, v97, v98, vcc
	v_cmp_class_f32_e32 vcc, v96, v147
	s_nop 1
	v_cndmask_b32_e32 v96, v97, v96, vcc
	v_div_scale_f32 v97, s[4:5], v96, v96, 0.5
	v_rcp_f32_e32 v98, v97
	s_nop 0
	v_fma_f32 v99, -v97, v98, 1.0
	v_fmac_f32_e32 v98, v99, v98
	v_div_scale_f32 v99, vcc, 0.5, v96, 0.5
	v_mul_f32_e32 v100, v99, v98
	v_fma_f32 v101, -v97, v100, v99
	v_fmac_f32_e32 v100, v101, v98
	v_fma_f32 v97, -v97, v100, v99
	v_div_fmas_f32 v97, v97, v98, v100
	v_div_fixup_f32 v96, v97, v96, 0.5
	v_mul_f32_e32 v0, v0, v96
	v_mul_f32_e32 v1, v1, v96
	v_mul_f32_e32 v2, v2, v96
	v_mul_f32_e32 v3, v3, v96
	v_mul_f32_e32 v4, v4, v96
	v_mul_f32_e32 v5, v5, v96
	v_mul_f32_e32 v6, v6, v96
	v_mul_f32_e32 v7, v7, v96
	v_mul_f32_e32 v8, v8, v96
	v_mul_f32_e32 v9, v9, v96
	v_mul_f32_e32 v10, v10, v96
	v_mul_f32_e32 v11, v11, v96
	v_mul_f32_e32 v12, v12, v96
	v_mul_f32_e32 v13, v13, v96
	v_mul_f32_e32 v14, v14, v96
	v_mul_f32_e32 v15, v15, v96
	v_fmac_f32_e32 v16, v112, v0
	v_fmac_f32_e32 v17, v113, v1
	v_fmac_f32_e32 v18, v114, v2
	v_fmac_f32_e32 v19, v115, v3
	v_fmac_f32_e32 v20, v116, v4
	v_fmac_f32_e32 v21, v117, v5
	v_fmac_f32_e32 v22, v118, v6
	v_fmac_f32_e32 v23, v119, v7
	v_fmac_f32_e32 v24, v120, v8
	v_fmac_f32_e32 v25, v121, v9
	v_fmac_f32_e32 v26, v122, v10
	v_fmac_f32_e32 v27, v123, v11
	v_fmac_f32_e32 v28, v124, v12
	v_fmac_f32_e32 v29, v125, v13
	v_fmac_f32_e32 v30, v126, v14
	v_fmac_f32_e32 v31, v127, v15
	global_store_dwordx4 v144, v[16:19], s[40:41] offset:0
	global_store_dwordx4 v144, v[20:23], s[40:41] offset:1024
	global_store_dwordx4 v144, v[24:27], s[40:41] offset:2048
	global_store_dwordx4 v144, v[28:31], s[40:41] offset:3072
	v_mul_f32_e32 v96, v17, v17
	v_mul_f32_e32 v98, v19, v19
	v_fmac_f32_e32 v96, v16, v16
	v_fmac_f32_e32 v98, v18, v18
	v_add_f32_e32 v96, v96, v98
	v_mul_f32_e32 v97, v21, v21
	v_mul_f32_e32 v98, v23, v23
	v_fmac_f32_e32 v97, v20, v20
	v_fmac_f32_e32 v98, v22, v22
	v_add_f32_e32 v97, v97, v98
	v_add_f32_e32 v96, v97, v96
	v_mul_f32_e32 v97, v25, v25
	v_mul_f32_e32 v98, v27, v27
	v_fmac_f32_e32 v97, v24, v24
	v_fmac_f32_e32 v98, v26, v26
	v_add_f32_e32 v97, v97, v98
	v_add_f32_e32 v96, v97, v96
	v_mul_f32_e32 v97, v29, v29
	v_mul_f32_e32 v98, v31, v31
	v_fmac_f32_e32 v97, v28, v28
; __device__ __forceinline__ unsigned pk2(float lo, float hi) { f32x2 v = {lo, hi}; bf16x2_t b = __builtin_convertvector(v, bf16x2_t); return __builtin_bit_cast(unsigned, b); }
; __device__ __forceinline__ void phase_rowpass(const Ctx& p, const float* F, int base_is_x, float alpha, const float* gpost, const float* gnext, bf16_t* XN, const float* PART, int nsplit) {
;     ...
;     for (int m = gw; m < MR; m += NGW) {
;         const bool more = m + NGW < MR;
;         if (more) loadrow(m + NGW, f2, b2);
;         float s = 0.f;
; #pragma unroll
;         for (int j = 0; j < 4; ++j) s += (f[j].x * f[j].x + f[j].y * f[j].y) + (f[j].z * f[j].z + f[j].w * f[j].w);
;         const float rs = alpha / sqrtf(wave_sum_fast(s) * (1.f / DM) + EPS);
;         float s2 = 0.f;
; #pragma unroll
;         for (int j = 0; j < 4; ++j) { b[j] = b[j] + f[j] * rs * gp[j]; s2 += (b[j].x * b[j].x + b[j].y * b[j].y) + (b[j].z * b[j].z + b[j].w * b[j].w);
;             ((f32x4*)(H + (size_t)m * DM))[lane + 64 * j] = b[j]; }
;         if (gnext) {
;             const float r2 = 1.f / sqrtf(wave_sum_fast(s2) * (1.f / DM) + EPS);
;             u32x2* o8 = (u32x2*)(XN + (size_t)m * DM) + lane;
; #pragma unroll
;             for (int j = 0; j < 4; ++j) { u32x2 w; w.x = pk2(b[j].x * r2 * gn[j].x, b[j].y * r2 * gn[j].y); w.y = pk2(b[j].z * r2 * gn[j].z, b[j].w * r2 * gn[j].w); o8[64 * j] = w; }
;         }
;         if (more) {
; #pragma unroll
;             for (int j = 0; j < 4; ++j) { f[j] = f2[j]; b[j] = b2[j]; } }
	v_fmac_f32_e32 v98, v30, v30
	v_add_f32_e32 v97, v97, v98
	v_add_f32_e32 v96, v97, v96
	s_nop 1
	v_add_f32_dpp v96, v96, v96 quad_perm:[1,0,3,2] row_mask:0xf bank_mask:0xf bound_ctrl:1
	s_nop 1
	v_add_f32_dpp v96, v96, v96 quad_perm:[2,3,0,1] row_mask:0xf bank_mask:0xf bound_ctrl:1
	s_nop 1
	v_add_f32_dpp v96, v96, v96 row_half_mirror row_mask:0xf bank_mask:0xf bound_ctrl:1
	s_nop 1
	v_add_f32_dpp v96, v96, v96 row_mirror row_mask:0xf bank_mask:0xf bound_ctrl:1
	v_mov_b32_e32 v97, v96
	s_nop 1
	v_permlane16_swap_b32_e32 v96, v97
	v_add_f32_e32 v96, v96, v97
	v_mov_b32_e32 v97, v96
	s_nop 1
	v_permlane32_swap_b32_e32 v96, v97
	v_add_f32_e32 v96, v96, v97
	v_fmamk_f32 v96, v96, 0x3a800000, v146
	v_mul_f32_e32 v97, 0x4f800000, v96
	v_cmp_gt_f32_e32 vcc, s33, v96
	s_nop 1
	v_cndmask_b32_e32 v96, v96, v97, vcc
	v_sqrt_f32_e32 v97, v96
	s_nop 0
	v_add_u32_e32 v98, -1, v97
	v_fma_f32 v99, -v98, v97, v96
	v_cmp_ge_f32_e64 s[4:5], 0, v99
	v_add_u32_e32 v99, 1, v97
	s_nop 0
	v_cndmask_b32_e64 v98, v97, v98, s[4:5]
	v_fma_f32 v97, -v99, v97, v96
	v_cmp_lt_f32_e64 s[4:5], 0, v97
	s_nop 1
	v_cndmask_b32_e64 v97, v98, v99, s[4:5]
	v_mul_f32_e32 v98, 0x37800000, v97
	v_cndmask_b32_e32 v97, v97, v98, vcc
	v_cmp_class_f32_e32 vcc, v96, v147
	s_nop 1
	v_cndmask_b32_e32 v96, v97, v96, vcc
	v_div_scale_f32 v97, s[4:5], v96, v96, 1.0
	v_rcp_f32_e32 v98, v97
	s_nop 0
	v_fma_f32 v99, -v97, v98, 1.0
	v_fmac_f32_e32 v98, v99, v98
	v_div_scale_f32 v99, vcc, 1.0, v96, 1.0
	v_mul_f32_e32 v100, v99, v98
	v_fma_f32 v101, -v97, v100, v99
	v_fmac_f32_e32 v100, v101, v98
	v_fma_f32 v97, -v97, v100, v99
	v_div_fmas_f32 v97, v97, v98, v100
	v_div_fixup_f32 v96, v97, v96, 1.0
	v_mul_f32_e32 v0, v16, v96
	v_mul_f32_e32 v1, v17, v96
	v_mul_f32_e32 v2, v18, v96
	v_mul_f32_e32 v3, v19, v96
	v_mul_f32_e32 v4, v20, v96
	v_mul_f32_e32 v5, v21, v96
	v_mul_f32_e32 v6, v22, v96
	v_mul_f32_e32 v7, v23, v96
	v_mul_f32_e32 v8, v24, v96
	v_mul_f32_e32 v9, v25, v96
	v_mul_f32_e32 v10, v26, v96
	v_mul_f32_e32 v11, v27, v96
	v_mul_f32_e32 v12, v28, v96
	v_mul_f32_e32 v13, v29, v96
	v_mul_f32_e32 v14, v30, v96
	v_mul_f32_e32 v15, v31, v96
	v_mul_f32_e32 v0, v128, v0
	v_mul_f32_e32 v1, v129, v1
	v_mul_f32_e32 v2, v130, v2
	v_mul_f32_e32 v3, v131, v3
	v_mul_f32_e32 v4, v132, v4
	v_mul_f32_e32 v5, v133, v5
	v_mul_f32_e32 v6, v134, v6
	v_mul_f32_e32 v7, v135, v7
	v_mul_f32_e32 v8, v136, v8
	v_mul_f32_e32 v9, v137, v9
	v_mul_f32_e32 v10, v138, v10
	v_mul_f32_e32 v11, v139, v11
	v_mul_f32_e32 v12, v140, v12
	v_mul_f32_e32 v13, v141, v13
	v_mul_f32_e32 v14, v142, v14
	v_mul_f32_e32 v15, v143, v15
	v_cvt_pk_bf16_f32 v148, v0, v1
	v_cvt_pk_bf16_f32 v149, v2, v3
	global_store_dwordx2 v145, v[148:149], s[42:43] offset:0
	v_cvt_pk_bf16_f32 v150, v4, v5
	v_cvt_pk_bf16_f32 v151, v6, v7
	global_store_dwordx2 v145, v[150:151], s[42:43] offset:512
	v_cvt_pk_bf16_f32 v152, v8, v9
	v_cvt_pk_bf16_f32 v153, v10, v11
	global_store_dwordx2 v145, v[152:153], s[42:43] offset:1024
	v_cvt_pk_bf16_f32 v154, v12, v13
	v_cvt_pk_bf16_f32 v155, v14, v15
	global_store_dwordx2 v145, v[154:155], s[42:43] offset:1536
	s_add_u32 s40, s40, 0x8000
	s_addc_u32 s41, s41, 0
	s_add_u32 s42, s42, 0x4000
	s_addc_u32 s43, s43, 0
	s_waitcnt vmcnt(16)
	v_mul_f32_e32 v96, v33, v33
	v_mul_f32_e32 v98, v35, v35
	v_fmac_f32_e32 v96, v32, v32
	v_fmac_f32_e32 v98, v34, v34
	v_add_f32_e32 v96, v96, v98
	v_mul_f32_e32 v97, v37, v37
	v_mul_f32_e32 v98, v39, v39
	v_fmac_f32_e32 v97, v36, v36
	v_fmac_f32_e32 v98, v38, v38
	v_add_f32_e32 v97, v97, v98
	v_add_f32_e32 v96, v97, v96
	v_mul_f32_e32 v97, v41, v41
	v_mul_f32_e32 v98, v43, v43
	v_fmac_f32_e32 v97, v40, v40
	v_fmac_f32_e32 v98, v42, v42
	v_add_f32_e32 v97, v97, v98
	v_add_f32_e32 v96, v97, v96
	v_mul_f32_e32 v97, v45, v45
	v_mul_f32_e32 v98, v47, v47
	v_fmac_f32_e32 v97, v44, v44
	v_fmac_f32_e32 v98, v46, v46
	v_add_f32_e32 v97, v97, v98
	v_add_f32_e32 v96, v97, v96
	s_nop 1
	v_add_f32_dpp v96, v96, v96 quad_perm:[1,0,3,2] row_mask:0xf bank_mask:0xf bound_ctrl:1
	s_nop 1
	v_add_f32_dpp v96, v96, v96 quad_perm:[2,3,0,1] row_mask:0xf bank_mask:0xf bound_ctrl:1
	s_nop 1
	v_add_f32_dpp v96, v96, v96 row_half_mirror row_mask:0xf bank_mask:0xf bound_ctrl:1
	s_nop 1
	v_add_f32_dpp v96, v96, v96 row_mirror row_mask:0xf bank_mask:0xf bound_ctrl:1
	v_mov_b32_e32 v97, v96
	s_nop 1
	v_permlane16_swap_b32_e32 v96, v97
	v_add_f32_e32 v96, v96, v97
	v_mov_b32_e32 v97, v96
	s_nop 1
	v_permlane32_swap_b32_e32 v96, v97
	v_add_f32_e32 v96, v96, v97
	v_fmamk_f32 v96, v96, 0x3a800000, v146
	v_mul_f32_e32 v97, 0x4f800000, v96
	v_cmp_gt_f32_e32 vcc, s33, v96
	s_nop 1
	v_cndmask_b32_e32 v96, v96, v97, vcc
	v_sqrt_f32_e32 v97, v96
	s_nop 0
	v_add_u32_e32 v98, -1, v97
	v_fma_f32 v99, -v98, v97, v96
	v_cmp_ge_f32_e64 s[4:5], 0, v99
	v_add_u32_e32 v99, 1, v97
	s_nop 0
	v_cndmask_b32_e64 v98, v97, v98, s[4:5]
	v_fma_f32 v97, -v99, v97, v96
	v_cmp_lt_f32_e64 s[4:5], 0, v97
	s_nop 1
	v_cndmask_b32_e64 v97, v98, v99, s[4:5]
	v_mul_f32_e32 v98, 0x37800000, v97
	v_cndmask_b32_e32 v97, v97, v98, vcc
	v_cmp_class_f32_e32 vcc, v96, v147
	s_nop 1
	v_cndmask_b32_e32 v96, v97, v96, vcc
	v_div_scale_f32 v97, s[4:5], v96, v96, 0.5
	v_rcp_f32_e32 v98, v97
	s_nop 0
	v_fma_f32 v99, -v97, v98, 1.0
	v_fmac_f32_e32 v98, v99, v98
	v_div_scale_f32 v99, vcc, 0.5, v96, 0.5
	v_mul_f32_e32 v100, v99, v98
	v_fma_f32 v101, -v97, v100, v99
	v_fmac_f32_e32 v100, v101, v98
; __device__ __forceinline__ unsigned pk2(float lo, float hi) { f32x2 v = {lo, hi}; bf16x2_t b = __builtin_convertvector(v, bf16x2_t); return __builtin_bit_cast(unsigned, b); }
; __device__ __forceinline__ void phase_rowpass(const Ctx& p, const float* F, int base_is_x, float alpha, const float* gpost, const float* gnext, bf16_t* XN, const float* PART, int nsplit) {
;     ...
;         float s = 0.f;
; #pragma unroll
;         for (int j = 0; j < 4; ++j) s += (f[j].x * f[j].x + f[j].y * f[j].y) + (f[j].z * f[j].z + f[j].w * f[j].w);
;         const float rs = alpha / sqrtf(wave_sum_fast(s) * (1.f / DM) + EPS);
;         float s2 = 0.f;
; #pragma unroll
;         for (int j = 0; j < 4; ++j) { b[j] = b[j] + f[j] * rs * gp[j]; s2 += (b[j].x * b[j].x + b[j].y * b[j].y) + (b[j].z * b[j].z + b[j].w * b[j].w);
;             ((f32x4*)(H + (size_t)m * DM))[lane + 64 * j] = b[j]; }
;         if (gnext) {
;             const float r2 = 1.f / sqrtf(wave_sum_fast(s2) * (1.f / DM) + EPS);
;             u32x2* o8 = (u32x2*)(XN + (size_t)m * DM) + lane;
; #pragma unroll
;             for (int j = 0; j < 4; ++j) { u32x2 w; w.x = pk2(b[j].x * r2 * gn[j].x, b[j].y * r2 * gn[j].y); w.y = pk2(b[j].z * r2 * gn[j].z, b[j].w * r2 * gn[j].w); o8[64 * j] = w; }
;         }
;         if (more) {
; #pragma unroll
;             for (int j = 0; j < 4; ++j) { f[j] = f2[j]; b[j] = b2[j]; } }
	v_fma_f32 v97, -v97, v100, v99
	v_div_fmas_f32 v97, v97, v98, v100
	v_div_fixup_f32 v96, v97, v96, 0.5
	v_mul_f32_e32 v32, v32, v96
	v_mul_f32_e32 v33, v33, v96
	v_mul_f32_e32 v34, v34, v96
	v_mul_f32_e32 v35, v35, v96
	v_mul_f32_e32 v36, v36, v96
	v_mul_f32_e32 v37, v37, v96
	v_mul_f32_e32 v38, v38, v96
	v_mul_f32_e32 v39, v39, v96
	v_mul_f32_e32 v40, v40, v96
	v_mul_f32_e32 v41, v41, v96
	v_mul_f32_e32 v42, v42, v96
	v_mul_f32_e32 v43, v43, v96
	v_mul_f32_e32 v44, v44, v96
	v_mul_f32_e32 v45, v45, v96
	v_mul_f32_e32 v46, v46, v96
	v_mul_f32_e32 v47, v47, v96
	v_fmac_f32_e32 v48, v112, v32
	v_fmac_f32_e32 v49, v113, v33
	v_fmac_f32_e32 v50, v114, v34
	v_fmac_f32_e32 v51, v115, v35
	v_fmac_f32_e32 v52, v116, v36
	v_fmac_f32_e32 v53, v117, v37
	v_fmac_f32_e32 v54, v118, v38
	v_fmac_f32_e32 v55, v119, v39
	v_fmac_f32_e32 v56, v120, v40
	v_fmac_f32_e32 v57, v121, v41
	v_fmac_f32_e32 v58, v122, v42
	v_fmac_f32_e32 v59, v123, v43
	v_fmac_f32_e32 v60, v124, v44
	v_fmac_f32_e32 v61, v125, v45
	v_fmac_f32_e32 v62, v126, v46
	v_fmac_f32_e32 v63, v127, v47
	global_store_dwordx4 v144, v[48:51], s[40:41] offset:0
	global_store_dwordx4 v144, v[52:55], s[40:41] offset:1024
	global_store_dwordx4 v144, v[56:59], s[40:41] offset:2048
	global_store_dwordx4 v144, v[60:63], s[40:41] offset:3072
	v_mul_f32_e32 v96, v49, v49
	v_mul_f32_e32 v98, v51, v51
	v_fmac_f32_e32 v96, v48, v48
	v_fmac_f32_e32 v98, v50, v50
	v_add_f32_e32 v96, v96, v98
	v_mul_f32_e32 v97, v53, v53
	v_mul_f32_e32 v98, v55, v55
	v_fmac_f32_e32 v97, v52, v52
	v_fmac_f32_e32 v98, v54, v54
	v_add_f32_e32 v97, v97, v98
	v_add_f32_e32 v96, v97, v96
	v_mul_f32_e32 v97, v57, v57
	v_mul_f32_e32 v98, v59, v59
	v_fmac_f32_e32 v97, v56, v56
	v_fmac_f32_e32 v98, v58, v58
	v_add_f32_e32 v97, v97, v98
	v_add_f32_e32 v96, v97, v96
	v_mul_f32_e32 v97, v61, v61
	v_mul_f32_e32 v98, v63, v63
	v_fmac_f32_e32 v97, v60, v60
	v_fmac_f32_e32 v98, v62, v62
	v_add_f32_e32 v97, v97, v98
	v_add_f32_e32 v96, v97, v96
	s_nop 1
	v_add_f32_dpp v96, v96, v96 quad_perm:[1,0,3,2] row_mask:0xf bank_mask:0xf bound_ctrl:1
	s_nop 1
	v_add_f32_dpp v96, v96, v96 quad_perm:[2,3,0,1] row_mask:0xf bank_mask:0xf bound_ctrl:1
	s_nop 1
	v_add_f32_dpp v96, v96, v96 row_half_mirror row_mask:0xf bank_mask:0xf bound_ctrl:1
	s_nop 1
	v_add_f32_dpp v96, v96, v96 row_mirror row_mask:0xf bank_mask:0xf bound_ctrl:1
	v_mov_b32_e32 v97, v96
	s_nop 1
	v_permlane16_swap_b32_e32 v96, v97
	v_add_f32_e32 v96, v96, v97
	v_mov_b32_e32 v97, v96
	s_nop 1
	v_permlane32_swap_b32_e32 v96, v97
	v_add_f32_e32 v96, v96, v97
	v_fmamk_f32 v96, v96, 0x3a800000, v146
	v_mul_f32_e32 v97, 0x4f800000, v96
	v_cmp_gt_f32_e32 vcc, s33, v96
	s_nop 1
	v_cndmask_b32_e32 v96, v96, v97, vcc
	v_sqrt_f32_e32 v97, v96
	s_nop 0
	v_add_u32_e32 v98, -1, v97
	v_fma_f32 v99, -v98, v97, v96
	v_cmp_ge_f32_e64 s[4:5], 0, v99
	v_add_u32_e32 v99, 1, v97
	s_nop 0
	v_cndmask_b32_e64 v98, v97, v98, s[4:5]
	v_fma_f32 v97, -v99, v97, v96
	v_cmp_lt_f32_e64 s[4:5], 0, v97
	s_nop 1
	v_cndmask_b32_e64 v97, v98, v99, s[4:5]
	v_mul_f32_e32 v98, 0x37800000, v97
	v_cndmask_b32_e32 v97, v97, v98, vcc
	v_cmp_class_f32_e32 vcc, v96, v147
	s_nop 1
	v_cndmask_b32_e32 v96, v97, v96, vcc
	v_div_scale_f32 v97, s[4:5], v96, v96, 1.0
	v_rcp_f32_e32 v98, v97
	s_nop 0
	v_fma_f32 v99, -v97, v98, 1.0
	v_fmac_f32_e32 v98, v99, v98
	v_div_scale_f32 v99, vcc, 1.0, v96, 1.0
	v_mul_f32_e32 v100, v99, v98
	v_fma_f32 v101, -v97, v100, v99
	v_fmac_f32_e32 v100, v101, v98
	v_fma_f32 v97, -v97, v100, v99
	v_div_fmas_f32 v97, v97, v98, v100
	v_div_fixup_f32 v96, v97, v96, 1.0
	v_mul_f32_e32 v32, v48, v96
	v_mul_f32_e32 v33, v49, v96
	v_mul_f32_e32 v34, v50, v96
	v_mul_f32_e32 v35, v51, v96
	v_mul_f32_e32 v36, v52, v96
	v_mul_f32_e32 v37, v53, v96
	v_mul_f32_e32 v38, v54, v96
	v_mul_f32_e32 v39, v55, v96
	v_mul_f32_e32 v40, v56, v96
	v_mul_f32_e32 v41, v57, v96
	v_mul_f32_e32 v42, v58, v96
	v_mul_f32_e32 v43, v59, v96
	v_mul_f32_e32 v44, v60, v96
	v_mul_f32_e32 v45, v61, v96
	v_mul_f32_e32 v46, v62, v96
	v_mul_f32_e32 v47, v63, v96
	v_mul_f32_e32 v32, v128, v32
	v_mul_f32_e32 v33, v129, v33
	v_mul_f32_e32 v34, v130, v34
	v_mul_f32_e32 v35, v131, v35
	v_mul_f32_e32 v36, v132, v36
	v_mul_f32_e32 v37, v133, v37
	v_mul_f32_e32 v38, v134, v38
	v_mul_f32_e32 v39, v135, v39
	v_mul_f32_e32 v40, v136, v40
	v_mul_f32_e32 v41, v137, v41
	v_mul_f32_e32 v42, v138, v42
	v_mul_f32_e32 v43, v139, v43
	v_mul_f32_e32 v44, v140, v44
	v_mul_f32_e32 v45, v141, v45
	v_mul_f32_e32 v46, v142, v46
	v_mul_f32_e32 v47, v143, v47
	v_cvt_pk_bf16_f32 v148, v32, v33
	v_cvt_pk_bf16_f32 v149, v34, v35
	global_store_dwordx2 v145, v[148:149], s[42:43] offset:0
	v_cvt_pk_bf16_f32 v150, v36, v37
	v_cvt_pk_bf16_f32 v151, v38, v39
	global_store_dwordx2 v145, v[150:151], s[42:43] offset:512
	v_cvt_pk_bf16_f32 v152, v40, v41
	v_cvt_pk_bf16_f32 v153, v42, v43
	global_store_dwordx2 v145, v[152:153], s[42:43] offset:1024
	v_cvt_pk_bf16_f32 v154, v44, v45
	v_cvt_pk_bf16_f32 v155, v46, v47
	global_store_dwordx2 v145, v[154:155], s[42:43] offset:1536
	s_add_u32 s40, s40, 0x8000
	s_addc_u32 s41, s41, 0
	s_add_u32 s42, s42, 0x4000
	s_addc_u32 s43, s43, 0
	s_sub_u32 s21, s28, 44
	s_cmp_lt_u32 s21, 16
	s_cbranch_scc0 .Lfrp3_end
	s_waitcnt vmcnt(0)
	v_cmp_eq_u32_e32 vcc, 0, v180
	s_and_saveexec_b64 s[46:47], vcc
	s_cbranch_execz .Lfrp3_ws_done
	v_mov_b32_e32 v230, 0
	s_add_u32 s44, s30, 0x3180500
	s_addc_u32 s45, s31, 0

; __device__ __forceinline__ unsigned xb_add(unsigned* p, unsigned v) { return __hip_atomic_fetch_add(p, v, __ATOMIC_RELAXED, __HIP_MEMORY_SCOPE_AGENT); }
; __device__ __forceinline__ void xcd_barrier(const XcdBarrier& b) {
;     asm volatile("s_waitcnt vmcnt(0)" ::: "memory");
;     __syncthreads();
;     if (threadIdx.x == 0) {
;         unsigned* bar = b.bar;
;         __builtin_amdgcn_s_waitcnt(0);
;         unsigned nloc = b.st[0], nx = b.st[1];
;         if (nloc == 0u) { xcd_barrier_complete(bar, b.x, nloc, nx); b.st[0] = nloc; b.st[1] = nx; }
;         const unsigned old = xb_add(&bar[XB_XSUB(b.x)], 1u);
.LBB0_447:
	s_nop 0
	s_cmp_gt_i32 s37, 4
	s_cselect_b64 s[2:3], -1, 0
	s_and_b64 s[4:5], s[6:7], s[2:3]
	s_andn2_b64 vcc, exec, s[4:5]
	s_cbranch_vccnz .LBB0_501
	s_waitcnt vmcnt(0)
	v_readlane_b32 s0, v238, 0
	v_readlane_b32 s1, v238, 1
	s_waitcnt vmcnt(0) lgkmcnt(0)
	s_barrier
	s_and_saveexec_b64 s[4:5], s[0:1]
	s_cbranch_execz .LBB0_500
	s_add_i32 s6, 0, 0x23800
	v_mov_b32_e32 v0, s6
	s_waitcnt vmcnt(0) expcnt(0) lgkmcnt(0)
	ds_read_b32 v2, v0
	s_add_i32 s6, 0, 0x23804
	v_mov_b32_e32 v0, s6
	ds_read_b32 v0, v0
	s_waitcnt lgkmcnt(1)
	v_cmp_ne_u32_e32 vcc, 0, v2
	s_cbranch_vccnz .LBB0_464
	s_add_u32 s6, s30, 0x3181200
	s_addc_u32 s7, s31, 0
	s_add_u32 s8, s30, 0x3181400
	s_addc_u32 s9, s31, 0
	s_add_u32 s10, s30, 0x3181500
	s_addc_u32 s11, s31, 0
	s_add_u32 s12, s30, 0x3181600
	s_addc_u32 s13, s31, 0
	s_add_u32 s14, s30, 0x3181700
	s_addc_u32 s15, s31, 0
	s_add_u32 s16, s30, 0x3181800
	s_addc_u32 s17, s31, 0
	s_add_u32 s18, s30, 0x3181900
	s_addc_u32 s19, s31, 0
	s_add_u32 s20, s30, 0x3181a00
	s_addc_u32 s21, s31, 0
	s_add_u32 s22, s30, 0x3181b00
	s_addc_u32 s23, s31, 0
	s_add_u32 s24, s30, 0x3181c00
	s_addc_u32 s25, s31, 0
	s_add_u32 s26, s30, 0x3181d00
	s_addc_u32 s27, s31, 0
	s_add_u32 s40, s30, 0x3181e00
	s_addc_u32 s41, s31, 0
	s_add_u32 s42, s30, 0x3181f00
	s_addc_u32 s43, s31, 0
	s_add_u32 s44, s30, 0x3182000
	s_addc_u32 s45, s31, 0
	s_add_u32 s46, s30, 0x3182100
	s_addc_u32 s47, s31, 0
	s_add_u32 s48, s30, 0x3182200
	s_addc_u32 s49, s31, 0
	s_mul_i32 s33, s39, s73
	s_add_u32 s50, s30, 0x3182300
	s_mul_i32 s33, s33, s38
	s_addc_u32 s51, s31, 0
	s_mov_b32 s34, 1
	v_mov_b32_e32 v16, 0
	s_branch .LBB0_452
